# IEEE f32 division sequences in GEMM epilogues (silu/gelu/sigmoid) replaced by v_rcp_f32+v_mul_f32 (still f32); attention stash in VGPRs
# speedup vs baseline: 1.0247x; 1.0247x over previous
.LBB0_231:
	s_cmp_gt_i32 s8, 1
	s_cselect_b64 s[12:13], -1, 0
	s_cmp_lg_u32 s8, 3
	s_cselect_b64 s[40:41], -1, 0
	s_add_i32 s7, s8, -3
	s_cmp_gt_u32 s7, 1
	s_cselect_b64 s[86:87], -1, 0
	s_lshl_b32 s27, s8, 8
	s_cmp_lg_u32 s8, 2
	s_cselect_b64 s[44:45], -1, 0
	s_cmp_gt_i32 s8, 8
	s_cselect_b64 s[46:47], -1, 0
	s_cmp_lt_i32 s8, 7
	s_movk_i32 s7, 0xfb00
	s_cselect_b32 s42, s7, 0xfffff900
	s_mov_b32 s7, 0x11700000
	s_cselect_b32 s7, s7, 0x12800000
	s_add_u32 s50, s14, s7
	s_addc_u32 s51, s15, 0
	s_cmp_eq_u32 s8, 3
	s_mov_b32 s7, 0x10b00000
	s_cselect_b32 s48, s7, 0x11300000
	s_mov_b32 s7, 0x10700000
	s_cselect_b32 s7, s7, 0x10f00000
	s_add_u32 s31, s14, s7
	s_addc_u32 s35, s15, 0
	s_lshl_b32 s64, s6, 8
	v_readlane_b32 s6, v255, 22
	s_add_i32 s64, s64, s6
	v_or_b32_e32 v172, s64, v155
	v_bitop3_b32 v183, s64, v240, v155 bitop3:0xc8
	v_cmp_gt_i32_e64 s[6:7], s76, v172
	v_or_b32_e32 v170, s27, v184
	v_lshl_add_u64 v[168:169], v[158:159], 0, s[48:49]
	v_cmp_lt_i32_e64 s[8:9], s79, v172
	s_ashr_i32 s26, s64, 13
	v_cndmask_b32_e64 v182, v177, v183, s[6:7]
	s_mov_b64 s[10:11], -1
	s_and_b64 vcc, exec, s[12:13]
	s_cbranch_vccz .LBB0_290
	v_add_u32_e32 v16, 0xffffc000, v172
	s_andn2_b64 vcc, exec, s[86:87]
	s_cbranch_vccnz .LBB0_262
	v_ashrrev_i32_e32 v173, 31, v172
	v_mov_b64_e32 v[130:131], s[14:15]
	s_movk_i32 s10, 0x60
	v_mad_i64_i32 v[136:137], s[10:11], v172, s10, v[130:131]
	v_lshlrev_b64 v[130:131], 10, v[172:173]
	v_lshl_add_u64 v[134:135], s[50:51], 0, v[130:131]
	s_mov_b64 s[10:11], -1
	s_and_b64 vcc, exec, s[44:45]
	s_cbranch_vccz .LBB0_249
	s_and_b64 vcc, exec, s[46:47]
	s_cbranch_vccz .LBB0_238
	s_movk_i32 s10, 0x918
	v_cmp_gt_i32_e32 vcc, s10, v170
	s_and_saveexec_b64 s[10:11], vcc
	s_cbranch_execz .LBB0_237
	v_mul_f32_e32 v132, 0xbfb8aa3b, v128
	v_mul_f32_e32 v133, 0xbfb8aa3b, v129
	v_exp_f32_e32 v132, v132
	v_exp_f32_e32 v133, v133
	v_mul_f32_e32 v130, 0xbfb8aa3b, v126
	v_mul_f32_e32 v131, 0xbfb8aa3b, v127
	v_exp_f32_e32 v130, v130
	v_pk_add_f32 v[132:133], v[132:133], 1.0 op_sel_hi:[1,0]
	v_exp_f32_e32 v131, v131
	v_div_scale_f32 v140, s[52:53], v133, v133, 1.0
	v_rcp_f32_e32 v141, v140
	v_pk_add_f32 v[130:131], v[130:131], 1.0 op_sel_hi:[1,0]
	v_mov_b32_e32 v171, v17
	v_lshl_add_u64 v[138:139], v[170:171], 2, v[136:137]
	v_fma_f32 v142, -v140, v141, 1.0
	v_fmac_f32_e32 v141, v142, v141
	v_div_scale_f32 v142, vcc, 1.0, v133, 1.0
	v_mul_f32_e32 v143, v142, v141
	v_fma_f32 v144, -v140, v143, v142
	v_fmac_f32_e32 v143, v144, v141
	v_fma_f32 v140, -v140, v143, v142
	v_div_fmas_f32 v140, v140, v141, v143
	v_div_fixup_f32 v133, v140, v133, 1.0
	v_rcp_f32_e32 v132, v132
	s_nop 0
	v_rcp_f32_e32 v131, v131
	s_nop 0
	v_div_scale_f32 v140, s[52:53], v130, v130, 1.0
	v_rcp_f32_e32 v141, v140
	s_nop 0
	v_fma_f32 v142, -v140, v141, 1.0
	v_fmac_f32_e32 v141, v142, v141
	v_div_scale_f32 v142, vcc, 1.0, v130, 1.0
	v_mul_f32_e32 v143, v142, v141
	v_fma_f32 v144, -v140, v143, v142
	v_fmac_f32_e32 v143, v144, v141
	v_fma_f32 v140, -v140, v143, v142
	v_div_fmas_f32 v140, v140, v141, v143
	v_mul_f32_e32 v142, 0xbfb8aa3b, v124
	v_mul_f32_e32 v143, 0xbfb8aa3b, v125
	v_exp_f32_e32 v142, v142
	v_exp_f32_e32 v143, v143
	v_div_fixup_f32 v130, v140, v130, 1.0
	v_mul_f32_e32 v140, 0xbfb8aa3b, v122
	v_mul_f32_e32 v141, 0xbfb8aa3b, v123
	v_pk_add_f32 v[142:143], v[142:143], 1.0 op_sel_hi:[1,0]
	v_exp_f32_e32 v140, v140
	v_div_scale_f32 v144, s[52:53], v143, v143, 1.0
	v_rcp_f32_e32 v145, v144
	v_exp_f32_e32 v141, v141
	v_fma_f32 v171, -v144, v145, 1.0
	v_fmac_f32_e32 v145, v171, v145
	v_div_scale_f32 v171, vcc, 1.0, v143, 1.0
	v_mul_f32_e32 v173, v171, v145
	v_fma_f32 v174, -v144, v173, v171
	v_fmac_f32_e32 v173, v174, v145
	v_fma_f32 v144, -v144, v173, v171
	v_div_fmas_f32 v144, v144, v145, v173
	v_div_fixup_f32 v143, v144, v143, 1.0
	v_div_scale_f32 v144, s[52:53], v142, v142, 1.0
	v_rcp_f32_e32 v145, v144
	v_pk_add_f32 v[140:141], v[140:141], 1.0 op_sel_hi:[1,0]
	v_fma_f32 v171, -v144, v145, 1.0
	v_fmac_f32_e32 v145, v171, v145
	v_div_scale_f32 v171, vcc, 1.0, v142, 1.0
	v_mul_f32_e32 v173, v171, v145
	v_fma_f32 v174, -v144, v173, v171
	v_fmac_f32_e32 v173, v174, v145
	v_fma_f32 v144, -v144, v173, v171
	v_div_fmas_f32 v144, v144, v145, v173
	v_div_fixup_f32 v142, v144, v142, 1.0
	v_rcp_f32_e32 v141, v141
	s_nop 0
	v_div_scale_f32 v144, s[52:53], v140, v140, 1.0
	v_rcp_f32_e32 v145, v144
	s_nop 0
	v_fma_f32 v171, -v144, v145, 1.0
	v_fmac_f32_e32 v145, v171, v145
	v_div_scale_f32 v171, vcc, 1.0, v140, 1.0
	v_mul_f32_e32 v173, v171, v145
	v_fma_f32 v174, -v144, v173, v171
	v_fmac_f32_e32 v173, v174, v145
	v_fma_f32 v144, -v144, v173, v171
	v_div_fmas_f32 v144, v144, v145, v173
	v_add_co_u32_e32 v138, vcc, 0x138fd000, v138
	v_div_fixup_f32 v140, v144, v140, 1.0
	s_nop 0
	v_addc_co_u32_e32 v139, vcc, 0, v139, vcc
	global_store_dwordx4 v[138:139], v[130:133], off offset:3072
	global_store_dwordx4 v[138:139], v[140:143], off offset:3088

.LBB0_238:
	s_andn2_b64 vcc, exec, s[10:11]
	s_cbranch_vccnz .LBB0_240
	v_mul_f32_e32 v131, 0x3d372713, v126
	v_mul_f32_e32 v131, v126, v131
	v_fma_f32 v131, v126, v131, v126
	v_mul_f32_e32 v131, 0xbfcc422a, v131
	v_mul_f32_e32 v131, 0x3fb8aa3b, v131
	v_exp_f32_e32 v131, v131
	v_add_u32_e32 v130, s42, v170
	v_add_f32_e32 v131, 1.0, v131
	v_rcp_f32_e32 v132, v131
	s_nop 0
	v_mul_f32_e32 v131, v126, v132
	v_mul_f32_e32 v132, 0x3d372713, v127
	v_mul_f32_e32 v132, v127, v132
	v_fma_f32 v132, v127, v132, v127
	v_mul_f32_e32 v132, 0xbfcc422a, v132
	v_mul_f32_e32 v132, 0x3fb8aa3b, v132
	v_exp_f32_e32 v132, v132
	s_nop 0
	v_add_f32_e32 v132, 1.0, v132
	v_rcp_f32_e32 v133, v132
	s_nop 0
	v_mul_f32_e32 v132, v127, v133
	v_mul_f32_e32 v133, 0x3d372713, v128
	v_mul_f32_e32 v133, v128, v133
	v_fma_f32 v133, v128, v133, v128
	v_mul_f32_e32 v133, 0xbfcc422a, v133
	v_mul_f32_e32 v133, 0x3fb8aa3b, v133
	v_exp_f32_e32 v133, v133
	s_nop 0
	v_add_f32_e32 v133, 1.0, v133
	v_rcp_f32_e32 v138, v133
	s_nop 0
	v_mul_f32_e32 v133, v128, v138
	v_mul_f32_e32 v138, 0x3d372713, v129
	v_mul_f32_e32 v138, v129, v138
	v_fma_f32 v138, v129, v138, v129
	v_mul_f32_e32 v138, 0xbfcc422a, v138
	v_mul_f32_e32 v138, 0x3fb8aa3b, v138
	v_exp_f32_e32 v138, v138
	s_nop 0
	v_add_f32_e32 v138, 1.0, v138
	v_rcp_f32_e32 v139, v138
	s_nop 0
	v_mul_f32_e32 v139, v129, v139
	v_mul_f32_e32 v138, 0x3d372713, v122
	v_mul_f32_e32 v138, v122, v138
	v_fma_f32 v138, v122, v138, v122
	v_mul_f32_e32 v138, 0xbfcc422a, v138
	v_mul_f32_e32 v138, 0x3fb8aa3b, v138
	v_exp_f32_e32 v138, v138
	s_nop 0
	v_add_f32_e32 v138, 1.0, v138
	v_rcp_f32_e32 v140, v138
	s_nop 0
	v_mul_f32_e32 v140, v122, v140
	v_mul_f32_e32 v138, 0x3d372713, v123
	v_mul_f32_e32 v138, v123, v138
	v_fma_f32 v138, v123, v138, v123
	v_mul_f32_e32 v138, 0xbfcc422a, v138
	v_mul_f32_e32 v138, 0x3fb8aa3b, v138
	v_exp_f32_e32 v138, v138
	s_nop 0
	v_add_f32_e32 v138, 1.0, v138
	v_rcp_f32_e32 v141, v138
	s_nop 0
	v_mul_f32_e32 v141, v123, v141
	v_mul_f32_e32 v138, 0x3d372713, v124
	v_mul_f32_e32 v138, v124, v138
	v_fma_f32 v138, v124, v138, v124
	v_mul_f32_e32 v138, 0xbfcc422a, v138
	v_mul_f32_e32 v138, 0x3fb8aa3b, v138
	v_exp_f32_e32 v138, v138
	s_nop 0
	v_add_f32_e32 v138, 1.0, v138
	v_rcp_f32_e32 v142, v138
	s_nop 0
	v_mul_f32_e32 v142, v124, v142
	v_mul_f32_e32 v138, 0x3d372713, v125
	v_mul_f32_e32 v138, v125, v138
	v_fma_f32 v138, v125, v138, v125
	v_mul_f32_e32 v138, 0xbfcc422a, v138
	v_mul_f32_e32 v138, 0x3fb8aa3b, v138
	v_exp_f32_e32 v138, v138
	s_nop 0
	v_add_f32_e32 v138, 1.0, v138
	v_rcp_f32_e32 v143, v138
	s_nop 0
	v_mul_f32_e32 v143, v125, v143
	v_cvt_pk_bf16_f32 v138, v131, v132
	v_ashrrev_i32_e32 v131, 31, v130
	v_lshl_add_u64 v[130:131], v[130:131], 1, v[134:135]
	v_cvt_pk_bf16_f32 v139, v133, v139
	v_cvt_pk_bf16_f32 v140, v140, v141
	v_cvt_pk_bf16_f32 v141, v142, v143
	global_store_dwordx4 v[130:131], v[138:141], off

.LBB0_242:
	s_andn2_b64 vcc, exec, s[46:47]
	s_cbranch_vccnz .LBB0_246
	v_or_b32_e32 v130, 0x80, v170
	s_movk_i32 s10, 0x918
	v_cmp_gt_i32_e32 vcc, s10, v130
	s_and_saveexec_b64 s[10:11], vcc
	s_cbranch_execz .LBB0_245
	v_mul_f32_e32 v132, 0xbfb8aa3b, v120
	v_mul_f32_e32 v133, 0xbfb8aa3b, v121
	v_exp_f32_e32 v132, v132
	v_exp_f32_e32 v133, v133
	v_mul_f32_e32 v130, 0xbfb8aa3b, v118
	v_mul_f32_e32 v131, 0xbfb8aa3b, v119
	v_exp_f32_e32 v130, v130
	v_pk_add_f32 v[132:133], v[132:133], 1.0 op_sel_hi:[1,0]
	v_exp_f32_e32 v131, v131
	v_div_scale_f32 v141, s[52:53], v133, v133, 1.0
	v_rcp_f32_e32 v142, v141
	v_pk_add_f32 v[130:131], v[130:131], 1.0 op_sel_hi:[1,0]
	v_mov_b32_e32 v171, v17
	v_lshl_add_u64 v[136:137], v[170:171], 2, v[136:137]
	v_fma_f32 v143, -v141, v142, 1.0
	v_fmac_f32_e32 v142, v143, v142
	v_div_scale_f32 v143, vcc, 1.0, v133, 1.0
	v_mul_f32_e32 v144, v143, v142
	v_fma_f32 v145, -v141, v144, v143
	v_fmac_f32_e32 v144, v145, v142
	v_fma_f32 v141, -v141, v144, v143
	v_div_fmas_f32 v141, v141, v142, v144
	v_div_fixup_f32 v133, v141, v133, 1.0
	v_rcp_f32_e32 v132, v132
	s_nop 0
	v_rcp_f32_e32 v131, v131
	s_nop 0
	v_rcp_f32_e32 v130, v130
	s_nop 0
	v_mul_f32_e32 v141, 0xbfb8aa3b, v114
	v_exp_f32_e32 v142, v141
	v_mul_f32_e32 v141, 0xbfb8aa3b, v115
	v_exp_f32_e32 v143, v141
	v_mul_f32_e32 v141, 0xbfb8aa3b, v116
	v_exp_f32_e32 v144, v141
	v_mul_f32_e32 v141, 0xbfb8aa3b, v117
	v_exp_f32_e32 v145, v141
	v_pk_add_f32 v[142:143], v[142:143], 1.0 op_sel_hi:[1,0]
	v_pk_add_f32 v[144:145], v[144:145], 1.0 op_sel_hi:[1,0]
	s_nop 0
	v_rcp_f32_e32 v145, v145
	s_nop 0
	v_rcp_f32_e32 v144, v144
	s_nop 0
	v_rcp_f32_e32 v143, v143
	s_nop 0
	v_div_scale_f32 v141, s[52:53], v142, v142, 1.0
	v_rcp_f32_e32 v171, v141
	s_nop 0
	v_fma_f32 v173, -v141, v171, 1.0
	v_fmac_f32_e32 v171, v173, v171
	v_div_scale_f32 v173, vcc, 1.0, v142, 1.0
	v_mul_f32_e32 v174, v173, v171
	v_fma_f32 v175, -v141, v174, v173
	v_fmac_f32_e32 v174, v175, v171
	v_fma_f32 v141, -v141, v174, v173
	v_div_fmas_f32 v141, v141, v171, v174
	v_add_co_u32_e32 v136, vcc, 0x138fd000, v136
	v_div_fixup_f32 v142, v141, v142, 1.0
	s_nop 0
	v_addc_co_u32_e32 v137, vcc, 0, v137, vcc
	global_store_dwordx4 v[136:137], v[130:133], off offset:3584
	global_store_dwordx4 v[136:137], v[142:145], off offset:3600

.LBB0_246:
	s_andn2_b64 vcc, exec, s[10:11]
	s_cbranch_vccnz .LBB0_248
	v_mul_f32_e32 v130, 0x3d372713, v118
	v_mul_f32_e32 v130, v118, v130
	v_fma_f32 v130, v118, v130, v118
	v_mul_f32_e32 v130, 0xbfcc422a, v130
	v_mul_f32_e32 v130, 0x3fb8aa3b, v130
	v_exp_f32_e32 v130, v130
	s_ashr_i32 s43, s42, 31
	v_add_f32_e32 v130, 1.0, v130
	v_rcp_f32_e32 v131, v130
	s_nop 0
	v_mul_f32_e32 v130, v118, v131
	v_mul_f32_e32 v131, 0x3d372713, v119
	v_mul_f32_e32 v131, v119, v131
	v_fma_f32 v131, v119, v131, v119
	v_mul_f32_e32 v131, 0xbfcc422a, v131
	v_mul_f32_e32 v131, 0x3fb8aa3b, v131
	v_exp_f32_e32 v131, v131
	s_nop 0
	v_add_f32_e32 v131, 1.0, v131
	v_rcp_f32_e32 v132, v131
	s_nop 0
	v_mul_f32_e32 v131, v119, v132
	v_mul_f32_e32 v132, 0x3d372713, v120
	v_mul_f32_e32 v132, v120, v132
	v_fma_f32 v132, v120, v132, v120
	v_mul_f32_e32 v132, 0xbfcc422a, v132
	v_mul_f32_e32 v132, 0x3fb8aa3b, v132
	v_exp_f32_e32 v132, v132
	v_cvt_pk_bf16_f32 v130, v130, v131
	s_nop 0
	v_add_f32_e32 v132, 1.0, v132
	v_rcp_f32_e32 v133, v132
	s_nop 0
	v_mul_f32_e32 v132, v120, v133
	v_mul_f32_e32 v133, 0x3d372713, v121
	v_mul_f32_e32 v133, v121, v133
	v_fma_f32 v133, v121, v133, v121
	v_mul_f32_e32 v133, 0xbfcc422a, v133
	v_mul_f32_e32 v133, 0x3fb8aa3b, v133
	v_exp_f32_e32 v133, v133
	s_nop 0
	v_add_f32_e32 v133, 1.0, v133
	v_rcp_f32_e32 v136, v133
	s_nop 0
	v_mul_f32_e32 v133, v121, v136
	v_mul_f32_e32 v136, 0x3d372713, v114
	v_mul_f32_e32 v136, v114, v136
	v_fma_f32 v136, v114, v136, v114
	v_mul_f32_e32 v136, 0xbfcc422a, v136
	v_mul_f32_e32 v136, 0x3fb8aa3b, v136
	v_exp_f32_e32 v136, v136
	v_cvt_pk_bf16_f32 v131, v132, v133
	s_nop 0
	v_add_f32_e32 v136, 1.0, v136
	v_rcp_f32_e32 v137, v136
	s_nop 0
	v_mul_f32_e32 v136, v114, v137
	v_mul_f32_e32 v137, 0x3d372713, v115
	v_mul_f32_e32 v137, v115, v137
	v_fma_f32 v137, v115, v137, v115
	v_mul_f32_e32 v137, 0xbfcc422a, v137
	v_mul_f32_e32 v137, 0x3fb8aa3b, v137
	v_exp_f32_e32 v137, v137
	s_nop 0
	v_add_f32_e32 v137, 1.0, v137
	v_rcp_f32_e32 v141, v137
	s_nop 0
	v_mul_f32_e32 v137, v115, v141
	v_mul_f32_e32 v141, 0x3d372713, v116
	v_mul_f32_e32 v141, v116, v141
	v_fma_f32 v141, v116, v141, v116
	v_mul_f32_e32 v141, 0xbfcc422a, v141
	v_mul_f32_e32 v141, 0x3fb8aa3b, v141
	v_exp_f32_e32 v141, v141
	v_cvt_pk_bf16_f32 v132, v136, v137
	s_nop 0
	v_add_f32_e32 v141, 1.0, v141
	v_rcp_f32_e32 v142, v141
	s_nop 0
	v_mul_f32_e32 v141, v116, v142
	v_mul_f32_e32 v142, 0x3d372713, v117
	v_mul_f32_e32 v142, v117, v142
	v_fma_f32 v142, v117, v142, v117
	v_mul_f32_e32 v142, 0xbfcc422a, v142
	v_mul_f32_e32 v142, 0x3fb8aa3b, v142
	v_exp_f32_e32 v142, v142
	s_nop 0
	v_add_f32_e32 v142, 1.0, v142
	v_div_scale_f32 v143, s[10:11], v142, v142, v117
	v_rcp_f32_e32 v144, v143
	s_nop 0
	v_fma_f32 v145, -v143, v144, 1.0
	v_fmac_f32_e32 v144, v145, v144
	v_div_scale_f32 v145, vcc, v117, v142, v117
	v_mul_f32_e32 v171, v145, v144
	v_fma_f32 v173, -v143, v171, v145
	v_fmac_f32_e32 v171, v173, v144
	v_fma_f32 v143, -v143, v171, v145
	v_div_fmas_f32 v143, v143, v144, v171
	v_ashrrev_i32_e32 v171, 31, v170
	v_lshl_add_u64 v[136:137], v[170:171], 0, s[42:43]
	v_readlane_b32 s43, v255, 41
	v_lshl_add_u64 v[134:135], v[136:137], 1, v[134:135]
	v_div_fixup_f32 v142, v143, v142, v117
	v_cvt_pk_bf16_f32 v133, v141, v142
	global_store_dwordx4 v[134:135], v[130:133], off offset:256

.LBB0_292:
	v_or_b32_e32 v132, s64, v185
	v_bitop3_b32 v137, s64, v241, v185 bitop3:0xc8
	v_cmp_gt_i32_e64 s[8:9], s76, v132
	v_cndmask_b32_e64 v16, 0, 1, s[12:13]
	v_cmp_lt_i32_e64 s[10:11], s79, v132
	v_cndmask_b32_e64 v136, v177, v137, s[8:9]
	v_cmp_ne_u32_e64 s[6:7], 1, v16
	s_andn2_b64 vcc, exec, s[12:13]
	s_mov_b64 s[12:13], -1
	s_cbranch_vccnz .LBB0_351
	v_add_u32_e32 v16, 0xffffc000, v132
	s_andn2_b64 vcc, exec, s[86:87]
	s_cbranch_vccnz .LBB0_323
	v_ashrrev_i32_e32 v133, 31, v132
	v_mov_b64_e32 v[114:115], s[14:15]
	s_movk_i32 s12, 0x60
	v_mad_i64_i32 v[120:121], s[12:13], v132, s12, v[114:115]
	v_lshlrev_b64 v[114:115], 10, v[132:133]
	v_lshl_add_u64 v[118:119], s[50:51], 0, v[114:115]
	v_cndmask_b32_e64 v114, 0, 1, s[44:45]
	v_cmp_ne_u32_e64 s[12:13], 1, v114
	s_andn2_b64 vcc, exec, s[44:45]
	s_mov_b64 s[52:53], -1
	s_cbranch_vccnz .LBB0_310
	s_andn2_b64 vcc, exec, s[46:47]
	s_cbranch_vccnz .LBB0_299
	s_movk_i32 s27, 0x918
	v_cmp_gt_i32_e32 vcc, s27, v170
	s_and_saveexec_b64 s[52:53], vcc
	s_cbranch_execz .LBB0_298
	v_mul_f32_e32 v116, 0xbfb8aa3b, v112
	v_mul_f32_e32 v117, 0xbfb8aa3b, v113
	v_exp_f32_e32 v116, v116
	v_exp_f32_e32 v117, v117
	v_mul_f32_e32 v114, 0xbfb8aa3b, v110
	v_mul_f32_e32 v115, 0xbfb8aa3b, v111
	v_exp_f32_e32 v114, v114
	v_pk_add_f32 v[116:117], v[116:117], 1.0 op_sel_hi:[1,0]
	v_exp_f32_e32 v115, v115
	v_div_scale_f32 v124, s[68:69], v117, v117, 1.0
	v_rcp_f32_e32 v125, v124
	v_pk_add_f32 v[114:115], v[114:115], 1.0 op_sel_hi:[1,0]
	v_mov_b32_e32 v171, v17
	v_lshl_add_u64 v[122:123], v[170:171], 2, v[120:121]
	v_fma_f32 v126, -v124, v125, 1.0
	v_fmac_f32_e32 v125, v126, v125
	v_div_scale_f32 v126, vcc, 1.0, v117, 1.0
	v_mul_f32_e32 v127, v126, v125
	v_fma_f32 v128, -v124, v127, v126
	v_fmac_f32_e32 v127, v128, v125
	v_fma_f32 v124, -v124, v127, v126
	v_div_fmas_f32 v124, v124, v125, v127
	v_div_fixup_f32 v117, v124, v117, 1.0
	v_rcp_f32_e32 v116, v116
	s_nop 0
	v_rcp_f32_e32 v115, v115
	s_nop 0
	v_div_scale_f32 v124, s[68:69], v114, v114, 1.0
	v_rcp_f32_e32 v125, v124
	s_nop 0
	v_fma_f32 v126, -v124, v125, 1.0
	v_fmac_f32_e32 v125, v126, v125
	v_div_scale_f32 v126, vcc, 1.0, v114, 1.0
	v_mul_f32_e32 v127, v126, v125
	v_fma_f32 v128, -v124, v127, v126
	v_fmac_f32_e32 v127, v128, v125
	v_fma_f32 v124, -v124, v127, v126
	v_div_fmas_f32 v124, v124, v125, v127
	v_mul_f32_e32 v126, 0xbfb8aa3b, v108
	v_mul_f32_e32 v127, 0xbfb8aa3b, v109
	v_exp_f32_e32 v126, v126
	v_exp_f32_e32 v127, v127
	v_div_fixup_f32 v114, v124, v114, 1.0
	v_mul_f32_e32 v124, 0xbfb8aa3b, v106
	v_mul_f32_e32 v125, 0xbfb8aa3b, v107
	v_pk_add_f32 v[126:127], v[126:127], 1.0 op_sel_hi:[1,0]
	v_exp_f32_e32 v124, v124
	v_div_scale_f32 v128, s[68:69], v127, v127, 1.0
	v_rcp_f32_e32 v129, v128
	v_exp_f32_e32 v125, v125
	v_fma_f32 v133, -v128, v129, 1.0
	v_fmac_f32_e32 v129, v133, v129
	v_div_scale_f32 v133, vcc, 1.0, v127, 1.0
	v_mul_f32_e32 v134, v133, v129
	v_fma_f32 v135, -v128, v134, v133
	v_fmac_f32_e32 v134, v135, v129
	v_fma_f32 v128, -v128, v134, v133
	v_div_fmas_f32 v128, v128, v129, v134
	v_div_fixup_f32 v127, v128, v127, 1.0
	v_div_scale_f32 v128, s[68:69], v126, v126, 1.0
	v_rcp_f32_e32 v129, v128
	v_pk_add_f32 v[124:125], v[124:125], 1.0 op_sel_hi:[1,0]
	v_fma_f32 v133, -v128, v129, 1.0
	v_fmac_f32_e32 v129, v133, v129
	v_div_scale_f32 v133, vcc, 1.0, v126, 1.0
	v_mul_f32_e32 v134, v133, v129
	v_fma_f32 v135, -v128, v134, v133
	v_fmac_f32_e32 v134, v135, v129
	v_fma_f32 v128, -v128, v134, v133
	v_div_fmas_f32 v128, v128, v129, v134
	v_div_fixup_f32 v126, v128, v126, 1.0
	v_rcp_f32_e32 v125, v125
	s_nop 0
	v_div_scale_f32 v128, s[68:69], v124, v124, 1.0
	v_rcp_f32_e32 v129, v128
	s_nop 0
	v_fma_f32 v133, -v128, v129, 1.0
	v_fmac_f32_e32 v129, v133, v129
	v_div_scale_f32 v133, vcc, 1.0, v124, 1.0
	v_mul_f32_e32 v134, v133, v129
	v_fma_f32 v135, -v128, v134, v133
	v_fmac_f32_e32 v134, v135, v129
	v_fma_f32 v128, -v128, v134, v133
	v_div_fmas_f32 v128, v128, v129, v134
	v_add_co_u32_e32 v122, vcc, 0x138fd000, v122
	v_div_fixup_f32 v124, v128, v124, 1.0
	s_nop 0
	v_addc_co_u32_e32 v123, vcc, 0, v123, vcc
	global_store_dwordx4 v[122:123], v[114:117], off offset:3072
	global_store_dwordx4 v[122:123], v[124:127], off offset:3088

.LBB0_299:
	s_andn2_b64 vcc, exec, s[52:53]
	s_cbranch_vccnz .LBB0_301
	v_mul_f32_e32 v115, 0x3d372713, v110
	v_mul_f32_e32 v115, v110, v115
	v_fma_f32 v115, v110, v115, v110
	v_mul_f32_e32 v115, 0xbfcc422a, v115
	v_mul_f32_e32 v115, 0x3fb8aa3b, v115
	v_exp_f32_e32 v115, v115
	v_add_u32_e32 v114, s42, v170
	v_add_f32_e32 v115, 1.0, v115
	v_rcp_f32_e32 v116, v115
	s_nop 0
	v_mul_f32_e32 v115, v110, v116
	v_mul_f32_e32 v116, 0x3d372713, v111
	v_mul_f32_e32 v116, v111, v116
	v_fma_f32 v116, v111, v116, v111
	v_mul_f32_e32 v116, 0xbfcc422a, v116
	v_mul_f32_e32 v116, 0x3fb8aa3b, v116
	v_exp_f32_e32 v116, v116
	s_nop 0
	v_add_f32_e32 v116, 1.0, v116
	v_rcp_f32_e32 v117, v116
	s_nop 0
	v_mul_f32_e32 v116, v111, v117
	v_mul_f32_e32 v117, 0x3d372713, v112
	v_mul_f32_e32 v117, v112, v117
	v_fma_f32 v117, v112, v117, v112
	v_mul_f32_e32 v117, 0xbfcc422a, v117
	v_mul_f32_e32 v117, 0x3fb8aa3b, v117
	v_exp_f32_e32 v117, v117
	s_nop 0
	v_add_f32_e32 v117, 1.0, v117
	v_rcp_f32_e32 v122, v117
	s_nop 0
	v_mul_f32_e32 v117, v112, v122
	v_mul_f32_e32 v122, 0x3d372713, v113
	v_mul_f32_e32 v122, v113, v122
	v_fma_f32 v122, v113, v122, v113
	v_mul_f32_e32 v122, 0xbfcc422a, v122
	v_mul_f32_e32 v122, 0x3fb8aa3b, v122
	v_exp_f32_e32 v122, v122
	s_nop 0
	v_add_f32_e32 v122, 1.0, v122
	v_rcp_f32_e32 v123, v122
	s_nop 0
	v_mul_f32_e32 v123, v113, v123
	v_mul_f32_e32 v122, 0x3d372713, v106
	v_mul_f32_e32 v122, v106, v122
	v_fma_f32 v122, v106, v122, v106
	v_mul_f32_e32 v122, 0xbfcc422a, v122
	v_mul_f32_e32 v122, 0x3fb8aa3b, v122
	v_exp_f32_e32 v122, v122
	s_nop 0
	v_add_f32_e32 v122, 1.0, v122
	v_rcp_f32_e32 v124, v122
	s_nop 0
	v_mul_f32_e32 v124, v106, v124
	v_mul_f32_e32 v122, 0x3d372713, v107
	v_mul_f32_e32 v122, v107, v122
	v_fma_f32 v122, v107, v122, v107
	v_mul_f32_e32 v122, 0xbfcc422a, v122
	v_mul_f32_e32 v122, 0x3fb8aa3b, v122
	v_exp_f32_e32 v122, v122
	s_nop 0
	v_add_f32_e32 v122, 1.0, v122
	v_rcp_f32_e32 v125, v122
	s_nop 0
	v_mul_f32_e32 v125, v107, v125
	v_mul_f32_e32 v122, 0x3d372713, v108
	v_mul_f32_e32 v122, v108, v122
	v_fma_f32 v122, v108, v122, v108
	v_mul_f32_e32 v122, 0xbfcc422a, v122
	v_mul_f32_e32 v122, 0x3fb8aa3b, v122
	v_exp_f32_e32 v122, v122
	s_nop 0
	v_add_f32_e32 v122, 1.0, v122
	v_rcp_f32_e32 v126, v122
	s_nop 0
	v_mul_f32_e32 v126, v108, v126
	v_mul_f32_e32 v122, 0x3d372713, v109
	v_mul_f32_e32 v122, v109, v122
	v_fma_f32 v122, v109, v122, v109
	v_mul_f32_e32 v122, 0xbfcc422a, v122
	v_mul_f32_e32 v122, 0x3fb8aa3b, v122
	v_exp_f32_e32 v122, v122
	s_nop 0
	v_add_f32_e32 v122, 1.0, v122
	v_rcp_f32_e32 v127, v122
	s_nop 0
	v_mul_f32_e32 v127, v109, v127
	v_cvt_pk_bf16_f32 v122, v115, v116
	v_ashrrev_i32_e32 v115, 31, v114
	v_lshl_add_u64 v[114:115], v[114:115], 1, v[118:119]
	v_cvt_pk_bf16_f32 v123, v117, v123
	v_cvt_pk_bf16_f32 v124, v124, v125
	v_cvt_pk_bf16_f32 v125, v126, v127
	global_store_dwordx4 v[114:115], v[122:125], off

.LBB0_303:
	s_andn2_b64 vcc, exec, s[46:47]
	s_cbranch_vccnz .LBB0_307
	v_or_b32_e32 v114, 0x80, v170
	s_movk_i32 s12, 0x918
	v_cmp_gt_i32_e32 vcc, s12, v114
	s_and_saveexec_b64 s[12:13], vcc
	s_cbranch_execz .LBB0_306
	v_mul_f32_e32 v116, 0xbfb8aa3b, v104
	v_mul_f32_e32 v117, 0xbfb8aa3b, v105
	v_exp_f32_e32 v116, v116
	v_exp_f32_e32 v117, v117
	v_mul_f32_e32 v114, 0xbfb8aa3b, v102
	v_mul_f32_e32 v115, 0xbfb8aa3b, v103
	v_exp_f32_e32 v114, v114
	v_pk_add_f32 v[116:117], v[116:117], 1.0 op_sel_hi:[1,0]
	v_exp_f32_e32 v115, v115
	v_div_scale_f32 v125, s[52:53], v117, v117, 1.0
	v_rcp_f32_e32 v126, v125
	v_pk_add_f32 v[114:115], v[114:115], 1.0 op_sel_hi:[1,0]
	v_mov_b32_e32 v171, v17
	v_lshl_add_u64 v[120:121], v[170:171], 2, v[120:121]
	v_fma_f32 v127, -v125, v126, 1.0
	v_fmac_f32_e32 v126, v127, v126
	v_div_scale_f32 v127, vcc, 1.0, v117, 1.0
	v_mul_f32_e32 v128, v127, v126
	v_fma_f32 v129, -v125, v128, v127
	v_fmac_f32_e32 v128, v129, v126
	v_fma_f32 v125, -v125, v128, v127
	v_div_fmas_f32 v125, v125, v126, v128
	v_div_fixup_f32 v117, v125, v117, 1.0
	v_rcp_f32_e32 v116, v116
	s_nop 0
	v_rcp_f32_e32 v115, v115
	s_nop 0
	v_rcp_f32_e32 v114, v114
	s_nop 0
	v_mul_f32_e32 v125, 0xbfb8aa3b, v98
	v_exp_f32_e32 v126, v125
	v_mul_f32_e32 v125, 0xbfb8aa3b, v99
	v_exp_f32_e32 v127, v125
	v_mul_f32_e32 v125, 0xbfb8aa3b, v100
	v_exp_f32_e32 v128, v125
	v_mul_f32_e32 v125, 0xbfb8aa3b, v101
	v_exp_f32_e32 v129, v125
	v_pk_add_f32 v[126:127], v[126:127], 1.0 op_sel_hi:[1,0]
	v_pk_add_f32 v[128:129], v[128:129], 1.0 op_sel_hi:[1,0]
	s_nop 0
	v_rcp_f32_e32 v129, v129
	s_nop 0
	v_rcp_f32_e32 v128, v128
	s_nop 0
	v_rcp_f32_e32 v127, v127
	s_nop 0
	v_div_scale_f32 v125, s[52:53], v126, v126, 1.0
	v_rcp_f32_e32 v133, v125
	s_nop 0
	v_fma_f32 v134, -v125, v133, 1.0
	v_fmac_f32_e32 v133, v134, v133
	v_div_scale_f32 v134, vcc, 1.0, v126, 1.0
	v_mul_f32_e32 v135, v134, v133
	v_fma_f32 v138, -v125, v135, v134
	v_fmac_f32_e32 v135, v138, v133
	v_fma_f32 v125, -v125, v135, v134
	v_div_fmas_f32 v125, v125, v133, v135
	v_add_co_u32_e32 v120, vcc, 0x138fd000, v120
	v_div_fixup_f32 v126, v125, v126, 1.0
	s_nop 0
	v_addc_co_u32_e32 v121, vcc, 0, v121, vcc
	global_store_dwordx4 v[120:121], v[114:117], off offset:3584
	global_store_dwordx4 v[120:121], v[126:129], off offset:3600

.LBB0_307:
	s_andn2_b64 vcc, exec, s[12:13]
	s_cbranch_vccnz .LBB0_309
	v_mul_f32_e32 v114, 0x3d372713, v102
	v_mul_f32_e32 v114, v102, v114
	v_fma_f32 v114, v102, v114, v102
	v_mul_f32_e32 v114, 0xbfcc422a, v114
	v_mul_f32_e32 v114, 0x3fb8aa3b, v114
	v_exp_f32_e32 v114, v114
	s_ashr_i32 s43, s42, 31
	v_ashrrev_i32_e32 v171, 31, v170
	v_add_f32_e32 v114, 1.0, v114
	v_rcp_f32_e32 v115, v114
	s_nop 0
	v_mul_f32_e32 v114, v102, v115
	v_mul_f32_e32 v115, 0x3d372713, v103
	v_mul_f32_e32 v115, v103, v115
	v_fma_f32 v115, v103, v115, v103
	v_mul_f32_e32 v115, 0xbfcc422a, v115
	v_mul_f32_e32 v115, 0x3fb8aa3b, v115
	v_exp_f32_e32 v115, v115
	s_nop 0
	v_add_f32_e32 v115, 1.0, v115
	v_rcp_f32_e32 v116, v115
	s_nop 0
	v_mul_f32_e32 v115, v103, v116
	v_mul_f32_e32 v116, 0x3d372713, v104
	v_mul_f32_e32 v116, v104, v116
	v_fma_f32 v116, v104, v116, v104
	v_mul_f32_e32 v116, 0xbfcc422a, v116
	v_mul_f32_e32 v116, 0x3fb8aa3b, v116
	v_exp_f32_e32 v116, v116
	v_cvt_pk_bf16_f32 v114, v114, v115
	s_nop 0
	v_add_f32_e32 v116, 1.0, v116
	v_rcp_f32_e32 v117, v116
	s_nop 0
	v_mul_f32_e32 v116, v104, v117
	v_mul_f32_e32 v117, 0x3d372713, v105
	v_mul_f32_e32 v117, v105, v117
	v_fma_f32 v117, v105, v117, v105
	v_mul_f32_e32 v117, 0xbfcc422a, v117
	v_mul_f32_e32 v117, 0x3fb8aa3b, v117
	v_exp_f32_e32 v117, v117
	s_nop 0
	v_add_f32_e32 v117, 1.0, v117
	v_rcp_f32_e32 v120, v117
	s_nop 0
	v_mul_f32_e32 v117, v105, v120
	v_mul_f32_e32 v120, 0x3d372713, v98
	v_mul_f32_e32 v120, v98, v120
	v_fma_f32 v120, v98, v120, v98
	v_mul_f32_e32 v120, 0xbfcc422a, v120
	v_mul_f32_e32 v120, 0x3fb8aa3b, v120
	v_exp_f32_e32 v120, v120
	v_cvt_pk_bf16_f32 v115, v116, v117
	s_nop 0
	v_add_f32_e32 v120, 1.0, v120
	v_rcp_f32_e32 v121, v120
	s_nop 0
	v_mul_f32_e32 v120, v98, v121
	v_mul_f32_e32 v121, 0x3d372713, v99
	v_mul_f32_e32 v121, v99, v121
	v_fma_f32 v121, v99, v121, v99
	v_mul_f32_e32 v121, 0xbfcc422a, v121
	v_mul_f32_e32 v121, 0x3fb8aa3b, v121
	v_exp_f32_e32 v121, v121
	s_nop 0
	v_add_f32_e32 v121, 1.0, v121
	v_rcp_f32_e32 v125, v121
	s_nop 0
	v_mul_f32_e32 v121, v99, v125
	v_mul_f32_e32 v125, 0x3d372713, v100
	v_mul_f32_e32 v125, v100, v125
	v_fma_f32 v125, v100, v125, v100
	v_mul_f32_e32 v125, 0xbfcc422a, v125
	v_mul_f32_e32 v125, 0x3fb8aa3b, v125
	v_exp_f32_e32 v125, v125
	v_cvt_pk_bf16_f32 v116, v120, v121
	v_lshl_add_u64 v[120:121], v[170:171], 0, s[42:43]
	v_readlane_b32 s43, v255, 41
	v_add_f32_e32 v125, 1.0, v125
	v_div_scale_f32 v126, s[12:13], v125, v125, v100
	v_rcp_f32_e32 v127, v126
	v_lshl_add_u64 v[118:119], v[120:121], 1, v[118:119]
	v_fma_f32 v128, -v126, v127, 1.0
	v_fmac_f32_e32 v127, v128, v127
	v_div_scale_f32 v128, vcc, v100, v125, v100
	v_mul_f32_e32 v129, v128, v127
	v_fma_f32 v133, -v126, v129, v128
	v_fmac_f32_e32 v129, v133, v127
	v_fma_f32 v126, -v126, v129, v128
	v_div_fmas_f32 v126, v126, v127, v129
	v_div_fixup_f32 v125, v126, v125, v100
	v_mul_f32_e32 v126, 0x3d372713, v101
	v_mul_f32_e32 v126, v101, v126
	v_fma_f32 v126, v101, v126, v101
	v_mul_f32_e32 v126, 0xbfcc422a, v126
	v_mul_f32_e32 v126, 0x3fb8aa3b, v126
	v_exp_f32_e32 v126, v126
	s_nop 0
	v_add_f32_e32 v126, 1.0, v126
	v_rcp_f32_e32 v127, v126
	s_nop 0
	v_mul_f32_e32 v126, v101, v127
	v_cvt_pk_bf16_f32 v117, v125, v126
	global_store_dwordx4 v[118:119], v[114:117], off offset:256

.LBB0_353:
	v_or_b32_e32 v114, s64, v186
	v_bitop3_b32 v119, s64, v242, v186 bitop3:0xc8
	v_cmp_gt_i32_e64 s[8:9], s76, v114
	v_cmp_lt_i32_e64 s[10:11], s79, v114
	s_and_b64 vcc, exec, s[6:7]
	v_cndmask_b32_e64 v118, v177, v119, s[8:9]
	s_mov_b64 s[12:13], -1
	s_cbranch_vccnz .LBB0_412
	v_add_u32_e32 v16, 0xffffc000, v114
	s_andn2_b64 vcc, exec, s[86:87]
	s_cbranch_vccnz .LBB0_384
	v_ashrrev_i32_e32 v115, 31, v114
	v_mov_b64_e32 v[98:99], s[14:15]
	s_movk_i32 s12, 0x60
	v_mad_i64_i32 v[104:105], s[12:13], v114, s12, v[98:99]
	v_lshlrev_b64 v[98:99], 10, v[114:115]
	v_lshl_add_u64 v[102:103], s[50:51], 0, v[98:99]
	v_cndmask_b32_e64 v98, 0, 1, s[44:45]
	v_cmp_ne_u32_e64 s[12:13], 1, v98
	s_andn2_b64 vcc, exec, s[44:45]
	s_mov_b64 s[52:53], -1
	s_cbranch_vccnz .LBB0_371
	s_andn2_b64 vcc, exec, s[46:47]
	s_cbranch_vccnz .LBB0_360
	s_movk_i32 s27, 0x918
	v_cmp_gt_i32_e32 vcc, s27, v170
	s_and_saveexec_b64 s[52:53], vcc
	s_cbranch_execz .LBB0_359
	v_mul_f32_e32 v100, 0xbfb8aa3b, v96
	v_mul_f32_e32 v101, 0xbfb8aa3b, v97
	v_exp_f32_e32 v100, v100
	v_exp_f32_e32 v101, v101
	v_mul_f32_e32 v98, 0xbfb8aa3b, v94
	v_mul_f32_e32 v99, 0xbfb8aa3b, v95
	v_exp_f32_e32 v98, v98
	v_pk_add_f32 v[100:101], v[100:101], 1.0 op_sel_hi:[1,0]
	v_exp_f32_e32 v99, v99
	v_div_scale_f32 v108, s[68:69], v101, v101, 1.0
	v_rcp_f32_e32 v109, v108
	v_pk_add_f32 v[98:99], v[98:99], 1.0 op_sel_hi:[1,0]
	v_mov_b32_e32 v171, v17
	v_lshl_add_u64 v[106:107], v[170:171], 2, v[104:105]
	v_fma_f32 v110, -v108, v109, 1.0
	v_fmac_f32_e32 v109, v110, v109
	v_div_scale_f32 v110, vcc, 1.0, v101, 1.0
	v_mul_f32_e32 v111, v110, v109
	v_fma_f32 v112, -v108, v111, v110
	v_fmac_f32_e32 v111, v112, v109
	v_fma_f32 v108, -v108, v111, v110
	v_div_fmas_f32 v108, v108, v109, v111
	v_div_fixup_f32 v101, v108, v101, 1.0
	v_rcp_f32_e32 v100, v100
	s_nop 0
	v_rcp_f32_e32 v99, v99
	s_nop 0
	v_div_scale_f32 v108, s[68:69], v98, v98, 1.0
	v_rcp_f32_e32 v109, v108
	s_nop 0
	v_fma_f32 v110, -v108, v109, 1.0
	v_fmac_f32_e32 v109, v110, v109
	v_div_scale_f32 v110, vcc, 1.0, v98, 1.0
	v_mul_f32_e32 v111, v110, v109
	v_fma_f32 v112, -v108, v111, v110
	v_fmac_f32_e32 v111, v112, v109
	v_fma_f32 v108, -v108, v111, v110
	v_div_fmas_f32 v108, v108, v109, v111
	v_mul_f32_e32 v110, 0xbfb8aa3b, v92
	v_mul_f32_e32 v111, 0xbfb8aa3b, v93
	v_exp_f32_e32 v110, v110
	v_exp_f32_e32 v111, v111
	v_div_fixup_f32 v98, v108, v98, 1.0
	v_mul_f32_e32 v108, 0xbfb8aa3b, v90
	v_mul_f32_e32 v109, 0xbfb8aa3b, v91
	v_pk_add_f32 v[110:111], v[110:111], 1.0 op_sel_hi:[1,0]
	v_exp_f32_e32 v108, v108
	v_div_scale_f32 v112, s[68:69], v111, v111, 1.0
	v_rcp_f32_e32 v113, v112
	v_exp_f32_e32 v109, v109
	v_fma_f32 v115, -v112, v113, 1.0
	v_fmac_f32_e32 v113, v115, v113
	v_div_scale_f32 v115, vcc, 1.0, v111, 1.0
	v_mul_f32_e32 v116, v115, v113
	v_fma_f32 v117, -v112, v116, v115
	v_fmac_f32_e32 v116, v117, v113
	v_fma_f32 v112, -v112, v116, v115
	v_div_fmas_f32 v112, v112, v113, v116
	v_div_fixup_f32 v111, v112, v111, 1.0
	v_div_scale_f32 v112, s[68:69], v110, v110, 1.0
	v_rcp_f32_e32 v113, v112
	v_pk_add_f32 v[108:109], v[108:109], 1.0 op_sel_hi:[1,0]
	v_fma_f32 v115, -v112, v113, 1.0
	v_fmac_f32_e32 v113, v115, v113
	v_div_scale_f32 v115, vcc, 1.0, v110, 1.0
	v_mul_f32_e32 v116, v115, v113
	v_fma_f32 v117, -v112, v116, v115
	v_fmac_f32_e32 v116, v117, v113
	v_fma_f32 v112, -v112, v116, v115
	v_div_fmas_f32 v112, v112, v113, v116
	v_div_fixup_f32 v110, v112, v110, 1.0
	v_rcp_f32_e32 v109, v109
	s_nop 0
	v_div_scale_f32 v112, s[68:69], v108, v108, 1.0
	v_rcp_f32_e32 v113, v112
	s_nop 0
	v_fma_f32 v115, -v112, v113, 1.0
	v_fmac_f32_e32 v113, v115, v113
	v_div_scale_f32 v115, vcc, 1.0, v108, 1.0
	v_mul_f32_e32 v116, v115, v113
	v_fma_f32 v117, -v112, v116, v115
	v_fmac_f32_e32 v116, v117, v113
	v_fma_f32 v112, -v112, v116, v115
	v_div_fmas_f32 v112, v112, v113, v116
	v_add_co_u32_e32 v106, vcc, 0x138fd000, v106
	v_div_fixup_f32 v108, v112, v108, 1.0
	s_nop 0
	v_addc_co_u32_e32 v107, vcc, 0, v107, vcc
	global_store_dwordx4 v[106:107], v[98:101], off offset:3072
	global_store_dwordx4 v[106:107], v[108:111], off offset:3088

.LBB0_360:
	s_andn2_b64 vcc, exec, s[52:53]
	s_cbranch_vccnz .LBB0_362
	v_mul_f32_e32 v99, 0x3d372713, v94
	v_mul_f32_e32 v99, v94, v99
	v_fma_f32 v99, v94, v99, v94
	v_mul_f32_e32 v99, 0xbfcc422a, v99
	v_mul_f32_e32 v99, 0x3fb8aa3b, v99
	v_exp_f32_e32 v99, v99
	v_add_u32_e32 v98, s42, v170
	v_add_f32_e32 v99, 1.0, v99
	v_rcp_f32_e32 v100, v99
	s_nop 0
	v_mul_f32_e32 v99, v94, v100
	v_mul_f32_e32 v100, 0x3d372713, v95
	v_mul_f32_e32 v100, v95, v100
	v_fma_f32 v100, v95, v100, v95
	v_mul_f32_e32 v100, 0xbfcc422a, v100
	v_mul_f32_e32 v100, 0x3fb8aa3b, v100
	v_exp_f32_e32 v100, v100
	s_nop 0
	v_add_f32_e32 v100, 1.0, v100
	v_rcp_f32_e32 v101, v100
	s_nop 0
	v_mul_f32_e32 v100, v95, v101
	v_mul_f32_e32 v101, 0x3d372713, v96
	v_mul_f32_e32 v101, v96, v101
	v_fma_f32 v101, v96, v101, v96
	v_mul_f32_e32 v101, 0xbfcc422a, v101
	v_mul_f32_e32 v101, 0x3fb8aa3b, v101
	v_exp_f32_e32 v101, v101
	s_nop 0
	v_add_f32_e32 v101, 1.0, v101
	v_rcp_f32_e32 v106, v101
	s_nop 0
	v_mul_f32_e32 v101, v96, v106
	v_mul_f32_e32 v106, 0x3d372713, v97
	v_mul_f32_e32 v106, v97, v106
	v_fma_f32 v106, v97, v106, v97
	v_mul_f32_e32 v106, 0xbfcc422a, v106
	v_mul_f32_e32 v106, 0x3fb8aa3b, v106
	v_exp_f32_e32 v106, v106
	s_nop 0
	v_add_f32_e32 v106, 1.0, v106
	v_rcp_f32_e32 v107, v106
	s_nop 0
	v_mul_f32_e32 v107, v97, v107
	v_mul_f32_e32 v106, 0x3d372713, v90
	v_mul_f32_e32 v106, v90, v106
	v_fma_f32 v106, v90, v106, v90
	v_mul_f32_e32 v106, 0xbfcc422a, v106
	v_mul_f32_e32 v106, 0x3fb8aa3b, v106
	v_exp_f32_e32 v106, v106
	s_nop 0
	v_add_f32_e32 v106, 1.0, v106
	v_rcp_f32_e32 v108, v106
	s_nop 0
	v_mul_f32_e32 v108, v90, v108
	v_mul_f32_e32 v106, 0x3d372713, v91
	v_mul_f32_e32 v106, v91, v106
	v_fma_f32 v106, v91, v106, v91
	v_mul_f32_e32 v106, 0xbfcc422a, v106
	v_mul_f32_e32 v106, 0x3fb8aa3b, v106
	v_exp_f32_e32 v106, v106
	s_nop 0
	v_add_f32_e32 v106, 1.0, v106
	v_rcp_f32_e32 v109, v106
	s_nop 0
	v_mul_f32_e32 v109, v91, v109
	v_mul_f32_e32 v106, 0x3d372713, v92
	v_mul_f32_e32 v106, v92, v106
	v_fma_f32 v106, v92, v106, v92
	v_mul_f32_e32 v106, 0xbfcc422a, v106
	v_mul_f32_e32 v106, 0x3fb8aa3b, v106
	v_exp_f32_e32 v106, v106
	s_nop 0
	v_add_f32_e32 v106, 1.0, v106
	v_rcp_f32_e32 v110, v106
	s_nop 0
	v_mul_f32_e32 v110, v92, v110
	v_mul_f32_e32 v106, 0x3d372713, v93
	v_mul_f32_e32 v106, v93, v106
	v_fma_f32 v106, v93, v106, v93
	v_mul_f32_e32 v106, 0xbfcc422a, v106
	v_mul_f32_e32 v106, 0x3fb8aa3b, v106
	v_exp_f32_e32 v106, v106
	s_nop 0
	v_add_f32_e32 v106, 1.0, v106
	v_rcp_f32_e32 v111, v106
	s_nop 0
	v_mul_f32_e32 v111, v93, v111
	v_cvt_pk_bf16_f32 v106, v99, v100
	v_ashrrev_i32_e32 v99, 31, v98
	v_lshl_add_u64 v[98:99], v[98:99], 1, v[102:103]
	v_cvt_pk_bf16_f32 v107, v101, v107
	v_cvt_pk_bf16_f32 v108, v108, v109
	v_cvt_pk_bf16_f32 v109, v110, v111
	global_store_dwordx4 v[98:99], v[106:109], off

.LBB0_364:
	s_andn2_b64 vcc, exec, s[46:47]
	s_cbranch_vccnz .LBB0_368
	v_or_b32_e32 v98, 0x80, v170
	s_movk_i32 s12, 0x918
	v_cmp_gt_i32_e32 vcc, s12, v98
	s_and_saveexec_b64 s[12:13], vcc
	s_cbranch_execz .LBB0_367
	v_mul_f32_e32 v100, 0xbfb8aa3b, v88
	v_mul_f32_e32 v101, 0xbfb8aa3b, v89
	v_exp_f32_e32 v100, v100
	v_exp_f32_e32 v101, v101
	v_mul_f32_e32 v98, 0xbfb8aa3b, v86
	v_mul_f32_e32 v99, 0xbfb8aa3b, v87
	v_exp_f32_e32 v98, v98
	v_pk_add_f32 v[100:101], v[100:101], 1.0 op_sel_hi:[1,0]
	v_exp_f32_e32 v99, v99
	v_div_scale_f32 v109, s[52:53], v101, v101, 1.0
	v_rcp_f32_e32 v110, v109
	v_pk_add_f32 v[98:99], v[98:99], 1.0 op_sel_hi:[1,0]
	v_mov_b32_e32 v171, v17
	v_lshl_add_u64 v[104:105], v[170:171], 2, v[104:105]
	v_fma_f32 v111, -v109, v110, 1.0
	v_fmac_f32_e32 v110, v111, v110
	v_div_scale_f32 v111, vcc, 1.0, v101, 1.0
	v_mul_f32_e32 v112, v111, v110
	v_fma_f32 v113, -v109, v112, v111
	v_fmac_f32_e32 v112, v113, v110
	v_fma_f32 v109, -v109, v112, v111
	v_div_fmas_f32 v109, v109, v110, v112
	v_div_fixup_f32 v101, v109, v101, 1.0
	v_rcp_f32_e32 v100, v100
	s_nop 0
	v_rcp_f32_e32 v99, v99
	s_nop 0
	v_rcp_f32_e32 v98, v98
	s_nop 0
	v_mul_f32_e32 v109, 0xbfb8aa3b, v82
	v_exp_f32_e32 v110, v109
	v_mul_f32_e32 v109, 0xbfb8aa3b, v83
	v_exp_f32_e32 v111, v109
	v_mul_f32_e32 v109, 0xbfb8aa3b, v84
	v_exp_f32_e32 v112, v109
	v_mul_f32_e32 v109, 0xbfb8aa3b, v85
	v_exp_f32_e32 v113, v109
	v_pk_add_f32 v[110:111], v[110:111], 1.0 op_sel_hi:[1,0]
	v_pk_add_f32 v[112:113], v[112:113], 1.0 op_sel_hi:[1,0]
	s_nop 0
	v_rcp_f32_e32 v113, v113
	s_nop 0
	v_rcp_f32_e32 v112, v112
	s_nop 0
	v_rcp_f32_e32 v111, v111
	s_nop 0
	v_div_scale_f32 v109, s[52:53], v110, v110, 1.0
	v_rcp_f32_e32 v115, v109
	s_nop 0
	v_fma_f32 v116, -v109, v115, 1.0
	v_fmac_f32_e32 v115, v116, v115
	v_div_scale_f32 v116, vcc, 1.0, v110, 1.0
	v_mul_f32_e32 v117, v116, v115
	v_fma_f32 v120, -v109, v117, v116
	v_fmac_f32_e32 v117, v120, v115
	v_fma_f32 v109, -v109, v117, v116
	v_div_fmas_f32 v109, v109, v115, v117
	v_add_co_u32_e32 v104, vcc, 0x138fd000, v104
	v_div_fixup_f32 v110, v109, v110, 1.0
	s_nop 0
	v_addc_co_u32_e32 v105, vcc, 0, v105, vcc
	global_store_dwordx4 v[104:105], v[98:101], off offset:3584
	global_store_dwordx4 v[104:105], v[110:113], off offset:3600

.LBB0_368:
	s_andn2_b64 vcc, exec, s[12:13]
	s_cbranch_vccnz .LBB0_370
	v_mul_f32_e32 v98, 0x3d372713, v86
	v_mul_f32_e32 v98, v86, v98
	v_fma_f32 v98, v86, v98, v86
	v_mul_f32_e32 v98, 0xbfcc422a, v98
	v_mul_f32_e32 v98, 0x3fb8aa3b, v98
	v_exp_f32_e32 v98, v98
	s_ashr_i32 s43, s42, 31
	v_ashrrev_i32_e32 v171, 31, v170
	v_add_f32_e32 v98, 1.0, v98
	v_rcp_f32_e32 v99, v98
	s_nop 0
	v_mul_f32_e32 v98, v86, v99
	v_mul_f32_e32 v99, 0x3d372713, v87
	v_mul_f32_e32 v99, v87, v99
	v_fma_f32 v99, v87, v99, v87
	v_mul_f32_e32 v99, 0xbfcc422a, v99
	v_mul_f32_e32 v99, 0x3fb8aa3b, v99
	v_exp_f32_e32 v99, v99
	s_nop 0
	v_add_f32_e32 v99, 1.0, v99
	v_rcp_f32_e32 v100, v99
	s_nop 0
	v_mul_f32_e32 v99, v87, v100
	v_mul_f32_e32 v100, 0x3d372713, v88
	v_mul_f32_e32 v100, v88, v100
	v_fma_f32 v100, v88, v100, v88
	v_mul_f32_e32 v100, 0xbfcc422a, v100
	v_mul_f32_e32 v100, 0x3fb8aa3b, v100
	v_exp_f32_e32 v100, v100
	v_cvt_pk_bf16_f32 v98, v98, v99
	s_nop 0
	v_add_f32_e32 v100, 1.0, v100
	v_rcp_f32_e32 v101, v100
	s_nop 0
	v_mul_f32_e32 v100, v88, v101
	v_mul_f32_e32 v101, 0x3d372713, v89
	v_mul_f32_e32 v101, v89, v101
	v_fma_f32 v101, v89, v101, v89
	v_mul_f32_e32 v101, 0xbfcc422a, v101
	v_mul_f32_e32 v101, 0x3fb8aa3b, v101
	v_exp_f32_e32 v101, v101
	s_nop 0
	v_add_f32_e32 v101, 1.0, v101
	v_rcp_f32_e32 v104, v101
	s_nop 0
	v_mul_f32_e32 v101, v89, v104
	v_mul_f32_e32 v104, 0x3d372713, v82
	v_mul_f32_e32 v104, v82, v104
	v_fma_f32 v104, v82, v104, v82
	v_mul_f32_e32 v104, 0xbfcc422a, v104
	v_mul_f32_e32 v104, 0x3fb8aa3b, v104
	v_exp_f32_e32 v104, v104
	v_cvt_pk_bf16_f32 v99, v100, v101
	s_nop 0
	v_add_f32_e32 v104, 1.0, v104
	v_rcp_f32_e32 v105, v104
	s_nop 0
	v_mul_f32_e32 v104, v82, v105
	v_mul_f32_e32 v105, 0x3d372713, v83
	v_mul_f32_e32 v105, v83, v105
	v_fma_f32 v105, v83, v105, v83
	v_mul_f32_e32 v105, 0xbfcc422a, v105
	v_mul_f32_e32 v105, 0x3fb8aa3b, v105
	v_exp_f32_e32 v105, v105
	s_nop 0
	v_add_f32_e32 v105, 1.0, v105
	v_rcp_f32_e32 v109, v105
	s_nop 0
	v_mul_f32_e32 v105, v83, v109
	v_mul_f32_e32 v109, 0x3d372713, v84
	v_mul_f32_e32 v109, v84, v109
	v_fma_f32 v109, v84, v109, v84
	v_mul_f32_e32 v109, 0xbfcc422a, v109
	v_mul_f32_e32 v109, 0x3fb8aa3b, v109
	v_exp_f32_e32 v109, v109
	v_cvt_pk_bf16_f32 v100, v104, v105
	v_lshl_add_u64 v[104:105], v[170:171], 0, s[42:43]
	v_readlane_b32 s43, v255, 41
	v_add_f32_e32 v109, 1.0, v109
	v_div_scale_f32 v110, s[12:13], v109, v109, v84
	v_rcp_f32_e32 v111, v110
	v_lshl_add_u64 v[102:103], v[104:105], 1, v[102:103]
	v_fma_f32 v112, -v110, v111, 1.0
	v_fmac_f32_e32 v111, v112, v111
	v_div_scale_f32 v112, vcc, v84, v109, v84
	v_mul_f32_e32 v113, v112, v111
	v_fma_f32 v115, -v110, v113, v112
	v_fmac_f32_e32 v113, v115, v111
	v_fma_f32 v110, -v110, v113, v112
	v_div_fmas_f32 v110, v110, v111, v113
	v_div_fixup_f32 v109, v110, v109, v84
	v_mul_f32_e32 v110, 0x3d372713, v85
	v_mul_f32_e32 v110, v85, v110
	v_fma_f32 v110, v85, v110, v85
	v_mul_f32_e32 v110, 0xbfcc422a, v110
	v_mul_f32_e32 v110, 0x3fb8aa3b, v110
	v_exp_f32_e32 v110, v110
	s_nop 0
	v_add_f32_e32 v110, 1.0, v110
	v_rcp_f32_e32 v111, v110
	s_nop 0
	v_mul_f32_e32 v110, v85, v111
	v_cvt_pk_bf16_f32 v101, v109, v110
	global_store_dwordx4 v[102:103], v[98:101], off offset:256

.LBB0_414:
	v_or_b32_e32 v98, s64, v187
	v_bitop3_b32 v103, s64, v243, v187 bitop3:0xc8
	v_cmp_gt_i32_e64 s[8:9], s76, v98
	v_cmp_lt_i32_e64 s[10:11], s79, v98
	s_and_b64 vcc, exec, s[6:7]
	v_cndmask_b32_e64 v102, v177, v103, s[8:9]
	s_mov_b64 s[12:13], -1
	s_cbranch_vccnz .LBB0_473
	v_add_u32_e32 v16, 0xffffc000, v98
	s_andn2_b64 vcc, exec, s[86:87]
	s_cbranch_vccnz .LBB0_445
	v_ashrrev_i32_e32 v99, 31, v98
	v_mov_b64_e32 v[82:83], s[14:15]
	s_movk_i32 s12, 0x60
	v_mad_i64_i32 v[88:89], s[12:13], v98, s12, v[82:83]
	v_lshlrev_b64 v[82:83], 10, v[98:99]
	v_lshl_add_u64 v[86:87], s[50:51], 0, v[82:83]
	v_cndmask_b32_e64 v82, 0, 1, s[44:45]
	v_cmp_ne_u32_e64 s[12:13], 1, v82
	s_andn2_b64 vcc, exec, s[44:45]
	s_mov_b64 s[52:53], -1
	s_cbranch_vccnz .LBB0_432
	s_andn2_b64 vcc, exec, s[46:47]
	s_cbranch_vccnz .LBB0_421
	s_movk_i32 s27, 0x918
	v_cmp_gt_i32_e32 vcc, s27, v170
	s_and_saveexec_b64 s[52:53], vcc
	s_cbranch_execz .LBB0_420
	v_mul_f32_e32 v84, 0xbfb8aa3b, v80
	v_mul_f32_e32 v85, 0xbfb8aa3b, v81
	v_exp_f32_e32 v84, v84
	v_exp_f32_e32 v85, v85
	v_mul_f32_e32 v82, 0xbfb8aa3b, v78
	v_mul_f32_e32 v83, 0xbfb8aa3b, v79
	v_exp_f32_e32 v82, v82
	v_pk_add_f32 v[84:85], v[84:85], 1.0 op_sel_hi:[1,0]
	v_exp_f32_e32 v83, v83
	v_div_scale_f32 v92, s[68:69], v85, v85, 1.0
	v_rcp_f32_e32 v93, v92
	v_pk_add_f32 v[82:83], v[82:83], 1.0 op_sel_hi:[1,0]
	v_mov_b32_e32 v171, v17
	v_lshl_add_u64 v[90:91], v[170:171], 2, v[88:89]
	v_fma_f32 v94, -v92, v93, 1.0
	v_fmac_f32_e32 v93, v94, v93
	v_div_scale_f32 v94, vcc, 1.0, v85, 1.0
	v_mul_f32_e32 v95, v94, v93
	v_fma_f32 v96, -v92, v95, v94
	v_fmac_f32_e32 v95, v96, v93
	v_fma_f32 v92, -v92, v95, v94
	v_div_fmas_f32 v92, v92, v93, v95
	v_div_fixup_f32 v85, v92, v85, 1.0
	v_rcp_f32_e32 v84, v84
	s_nop 0
	v_rcp_f32_e32 v83, v83
	s_nop 0
	v_div_scale_f32 v92, s[68:69], v82, v82, 1.0
	v_rcp_f32_e32 v93, v92
	s_nop 0
	v_fma_f32 v94, -v92, v93, 1.0
	v_fmac_f32_e32 v93, v94, v93
	v_div_scale_f32 v94, vcc, 1.0, v82, 1.0
	v_mul_f32_e32 v95, v94, v93
	v_fma_f32 v96, -v92, v95, v94
	v_fmac_f32_e32 v95, v96, v93
	v_fma_f32 v92, -v92, v95, v94
	v_div_fmas_f32 v92, v92, v93, v95
	v_mul_f32_e32 v94, 0xbfb8aa3b, v76
	v_mul_f32_e32 v95, 0xbfb8aa3b, v77
	v_exp_f32_e32 v94, v94
	v_exp_f32_e32 v95, v95
	v_div_fixup_f32 v82, v92, v82, 1.0
	v_mul_f32_e32 v92, 0xbfb8aa3b, v74
	v_mul_f32_e32 v93, 0xbfb8aa3b, v75
	v_pk_add_f32 v[94:95], v[94:95], 1.0 op_sel_hi:[1,0]
	v_exp_f32_e32 v92, v92
	v_div_scale_f32 v96, s[68:69], v95, v95, 1.0
	v_rcp_f32_e32 v97, v96
	v_exp_f32_e32 v93, v93
	v_fma_f32 v99, -v96, v97, 1.0
	v_fmac_f32_e32 v97, v99, v97
	v_div_scale_f32 v99, vcc, 1.0, v95, 1.0
	v_mul_f32_e32 v100, v99, v97
	v_fma_f32 v101, -v96, v100, v99
	v_fmac_f32_e32 v100, v101, v97
	v_fma_f32 v96, -v96, v100, v99
	v_div_fmas_f32 v96, v96, v97, v100
	v_div_fixup_f32 v95, v96, v95, 1.0
	v_div_scale_f32 v96, s[68:69], v94, v94, 1.0
	v_rcp_f32_e32 v97, v96
	v_pk_add_f32 v[92:93], v[92:93], 1.0 op_sel_hi:[1,0]
	v_fma_f32 v99, -v96, v97, 1.0
	v_fmac_f32_e32 v97, v99, v97
	v_div_scale_f32 v99, vcc, 1.0, v94, 1.0
	v_mul_f32_e32 v100, v99, v97
	v_fma_f32 v101, -v96, v100, v99
	v_fmac_f32_e32 v100, v101, v97
	v_fma_f32 v96, -v96, v100, v99
	v_div_fmas_f32 v96, v96, v97, v100
	v_div_fixup_f32 v94, v96, v94, 1.0
	v_rcp_f32_e32 v93, v93
	s_nop 0
	v_div_scale_f32 v96, s[68:69], v92, v92, 1.0
	v_rcp_f32_e32 v97, v96
	s_nop 0
	v_fma_f32 v99, -v96, v97, 1.0
	v_fmac_f32_e32 v97, v99, v97
	v_div_scale_f32 v99, vcc, 1.0, v92, 1.0
	v_mul_f32_e32 v100, v99, v97
	v_fma_f32 v101, -v96, v100, v99
	v_fmac_f32_e32 v100, v101, v97
	v_fma_f32 v96, -v96, v100, v99
	v_div_fmas_f32 v96, v96, v97, v100
	v_add_co_u32_e32 v90, vcc, 0x138fd000, v90
	v_div_fixup_f32 v92, v96, v92, 1.0
	s_nop 0
	v_addc_co_u32_e32 v91, vcc, 0, v91, vcc
	global_store_dwordx4 v[90:91], v[82:85], off offset:3072
	global_store_dwordx4 v[90:91], v[92:95], off offset:3088

.LBB0_421:
	s_andn2_b64 vcc, exec, s[52:53]
	s_cbranch_vccnz .LBB0_423
	v_mul_f32_e32 v83, 0x3d372713, v78
	v_mul_f32_e32 v83, v78, v83
	v_fma_f32 v83, v78, v83, v78
	v_mul_f32_e32 v83, 0xbfcc422a, v83
	v_mul_f32_e32 v83, 0x3fb8aa3b, v83
	v_exp_f32_e32 v83, v83
	v_add_u32_e32 v82, s42, v170
	v_add_f32_e32 v83, 1.0, v83
	v_rcp_f32_e32 v84, v83
	s_nop 0
	v_mul_f32_e32 v83, v78, v84
	v_mul_f32_e32 v84, 0x3d372713, v79
	v_mul_f32_e32 v84, v79, v84
	v_fma_f32 v84, v79, v84, v79
	v_mul_f32_e32 v84, 0xbfcc422a, v84
	v_mul_f32_e32 v84, 0x3fb8aa3b, v84
	v_exp_f32_e32 v84, v84
	s_nop 0
	v_add_f32_e32 v84, 1.0, v84
	v_rcp_f32_e32 v85, v84
	s_nop 0
	v_mul_f32_e32 v84, v79, v85
	v_mul_f32_e32 v85, 0x3d372713, v80
	v_mul_f32_e32 v85, v80, v85
	v_fma_f32 v85, v80, v85, v80
	v_mul_f32_e32 v85, 0xbfcc422a, v85
	v_mul_f32_e32 v85, 0x3fb8aa3b, v85
	v_exp_f32_e32 v85, v85
	s_nop 0
	v_add_f32_e32 v85, 1.0, v85
	v_rcp_f32_e32 v90, v85
	s_nop 0
	v_mul_f32_e32 v85, v80, v90
	v_mul_f32_e32 v90, 0x3d372713, v81
	v_mul_f32_e32 v90, v81, v90
	v_fma_f32 v90, v81, v90, v81
	v_mul_f32_e32 v90, 0xbfcc422a, v90
	v_mul_f32_e32 v90, 0x3fb8aa3b, v90
	v_exp_f32_e32 v90, v90
	s_nop 0
	v_add_f32_e32 v90, 1.0, v90
	v_rcp_f32_e32 v91, v90
	s_nop 0
	v_mul_f32_e32 v91, v81, v91
	v_mul_f32_e32 v90, 0x3d372713, v74
	v_mul_f32_e32 v90, v74, v90
	v_fma_f32 v90, v74, v90, v74
	v_mul_f32_e32 v90, 0xbfcc422a, v90
	v_mul_f32_e32 v90, 0x3fb8aa3b, v90
	v_exp_f32_e32 v90, v90
	s_nop 0
	v_add_f32_e32 v90, 1.0, v90
	v_rcp_f32_e32 v92, v90
	s_nop 0
	v_mul_f32_e32 v92, v74, v92
	v_mul_f32_e32 v90, 0x3d372713, v75
	v_mul_f32_e32 v90, v75, v90
	v_fma_f32 v90, v75, v90, v75
	v_mul_f32_e32 v90, 0xbfcc422a, v90
	v_mul_f32_e32 v90, 0x3fb8aa3b, v90
	v_exp_f32_e32 v90, v90
	s_nop 0
	v_add_f32_e32 v90, 1.0, v90
	v_rcp_f32_e32 v93, v90
	s_nop 0
	v_mul_f32_e32 v93, v75, v93
	v_mul_f32_e32 v90, 0x3d372713, v76
	v_mul_f32_e32 v90, v76, v90
	v_fma_f32 v90, v76, v90, v76
	v_mul_f32_e32 v90, 0xbfcc422a, v90
	v_mul_f32_e32 v90, 0x3fb8aa3b, v90
	v_exp_f32_e32 v90, v90
	s_nop 0
	v_add_f32_e32 v90, 1.0, v90
	v_rcp_f32_e32 v94, v90
	s_nop 0
	v_mul_f32_e32 v94, v76, v94
	v_mul_f32_e32 v90, 0x3d372713, v77
	v_mul_f32_e32 v90, v77, v90
	v_fma_f32 v90, v77, v90, v77
	v_mul_f32_e32 v90, 0xbfcc422a, v90
	v_mul_f32_e32 v90, 0x3fb8aa3b, v90
	v_exp_f32_e32 v90, v90
	s_nop 0
	v_add_f32_e32 v90, 1.0, v90
	v_rcp_f32_e32 v95, v90
	s_nop 0
	v_mul_f32_e32 v95, v77, v95
	v_cvt_pk_bf16_f32 v90, v83, v84
	v_ashrrev_i32_e32 v83, 31, v82
	v_lshl_add_u64 v[82:83], v[82:83], 1, v[86:87]
	v_cvt_pk_bf16_f32 v91, v85, v91
	v_cvt_pk_bf16_f32 v92, v92, v93
	v_cvt_pk_bf16_f32 v93, v94, v95
	global_store_dwordx4 v[82:83], v[90:93], off

.LBB0_425:
	s_andn2_b64 vcc, exec, s[46:47]
	s_cbranch_vccnz .LBB0_429
	v_or_b32_e32 v82, 0x80, v170
	s_movk_i32 s12, 0x918
	v_cmp_gt_i32_e32 vcc, s12, v82
	s_and_saveexec_b64 s[12:13], vcc
	s_cbranch_execz .LBB0_428
	v_mul_f32_e32 v84, 0xbfb8aa3b, v72
	v_mul_f32_e32 v85, 0xbfb8aa3b, v73
	v_exp_f32_e32 v84, v84
	v_exp_f32_e32 v85, v85
	v_mul_f32_e32 v82, 0xbfb8aa3b, v70
	v_mul_f32_e32 v83, 0xbfb8aa3b, v71
	v_exp_f32_e32 v82, v82
	v_pk_add_f32 v[84:85], v[84:85], 1.0 op_sel_hi:[1,0]
	v_exp_f32_e32 v83, v83
	v_div_scale_f32 v93, s[52:53], v85, v85, 1.0
	v_rcp_f32_e32 v94, v93
	v_pk_add_f32 v[82:83], v[82:83], 1.0 op_sel_hi:[1,0]
	v_mov_b32_e32 v171, v17
	v_lshl_add_u64 v[88:89], v[170:171], 2, v[88:89]
	v_fma_f32 v95, -v93, v94, 1.0
	v_fmac_f32_e32 v94, v95, v94
	v_div_scale_f32 v95, vcc, 1.0, v85, 1.0
	v_mul_f32_e32 v96, v95, v94
	v_fma_f32 v97, -v93, v96, v95
	v_fmac_f32_e32 v96, v97, v94
	v_fma_f32 v93, -v93, v96, v95
	v_div_fmas_f32 v93, v93, v94, v96
	v_div_fixup_f32 v85, v93, v85, 1.0
	v_rcp_f32_e32 v84, v84
	s_nop 0
	v_rcp_f32_e32 v83, v83
	s_nop 0
	v_rcp_f32_e32 v82, v82
	s_nop 0
	v_mul_f32_e32 v93, 0xbfb8aa3b, v66
	v_exp_f32_e32 v94, v93
	v_mul_f32_e32 v93, 0xbfb8aa3b, v67
	v_exp_f32_e32 v95, v93
	v_mul_f32_e32 v93, 0xbfb8aa3b, v68
	v_exp_f32_e32 v96, v93
	v_mul_f32_e32 v93, 0xbfb8aa3b, v69
	v_exp_f32_e32 v97, v93
	v_pk_add_f32 v[94:95], v[94:95], 1.0 op_sel_hi:[1,0]
	v_pk_add_f32 v[96:97], v[96:97], 1.0 op_sel_hi:[1,0]
	s_nop 0
	v_rcp_f32_e32 v97, v97
	s_nop 0
	v_rcp_f32_e32 v96, v96
	s_nop 0
	v_rcp_f32_e32 v95, v95
	s_nop 0
	v_div_scale_f32 v93, s[52:53], v94, v94, 1.0
	v_rcp_f32_e32 v99, v93
	s_nop 0
	v_fma_f32 v100, -v93, v99, 1.0
	v_fmac_f32_e32 v99, v100, v99
	v_div_scale_f32 v100, vcc, 1.0, v94, 1.0
	v_mul_f32_e32 v101, v100, v99
	v_fma_f32 v104, -v93, v101, v100
	v_fmac_f32_e32 v101, v104, v99
	v_fma_f32 v93, -v93, v101, v100
	v_div_fmas_f32 v93, v93, v99, v101
	v_add_co_u32_e32 v88, vcc, 0x138fd000, v88
	v_div_fixup_f32 v94, v93, v94, 1.0
	s_nop 0
	v_addc_co_u32_e32 v89, vcc, 0, v89, vcc
	global_store_dwordx4 v[88:89], v[82:85], off offset:3584
	global_store_dwordx4 v[88:89], v[94:97], off offset:3600

.LBB0_429:
	s_andn2_b64 vcc, exec, s[12:13]
	s_cbranch_vccnz .LBB0_431
	v_mul_f32_e32 v82, 0x3d372713, v70
	v_mul_f32_e32 v82, v70, v82
	v_fma_f32 v82, v70, v82, v70
	v_mul_f32_e32 v82, 0xbfcc422a, v82
	v_mul_f32_e32 v82, 0x3fb8aa3b, v82
	v_exp_f32_e32 v82, v82
	s_ashr_i32 s43, s42, 31
	v_ashrrev_i32_e32 v171, 31, v170
	v_add_f32_e32 v82, 1.0, v82
	v_rcp_f32_e32 v83, v82
	s_nop 0
	v_mul_f32_e32 v82, v70, v83
	v_mul_f32_e32 v83, 0x3d372713, v71
	v_mul_f32_e32 v83, v71, v83
	v_fma_f32 v83, v71, v83, v71
	v_mul_f32_e32 v83, 0xbfcc422a, v83
	v_mul_f32_e32 v83, 0x3fb8aa3b, v83
	v_exp_f32_e32 v83, v83
	s_nop 0
	v_add_f32_e32 v83, 1.0, v83
	v_rcp_f32_e32 v84, v83
	s_nop 0
	v_mul_f32_e32 v83, v71, v84
	v_mul_f32_e32 v84, 0x3d372713, v72
	v_mul_f32_e32 v84, v72, v84
	v_fma_f32 v84, v72, v84, v72
	v_mul_f32_e32 v84, 0xbfcc422a, v84
	v_mul_f32_e32 v84, 0x3fb8aa3b, v84
	v_exp_f32_e32 v84, v84
	v_cvt_pk_bf16_f32 v82, v82, v83
	s_nop 0
	v_add_f32_e32 v84, 1.0, v84
	v_rcp_f32_e32 v85, v84
	s_nop 0
	v_mul_f32_e32 v84, v72, v85
	v_mul_f32_e32 v85, 0x3d372713, v73
	v_mul_f32_e32 v85, v73, v85
	v_fma_f32 v85, v73, v85, v73
	v_mul_f32_e32 v85, 0xbfcc422a, v85
	v_mul_f32_e32 v85, 0x3fb8aa3b, v85
	v_exp_f32_e32 v85, v85
	s_nop 0
	v_add_f32_e32 v85, 1.0, v85
	v_rcp_f32_e32 v88, v85
	s_nop 0
	v_mul_f32_e32 v85, v73, v88
	v_mul_f32_e32 v88, 0x3d372713, v66
	v_mul_f32_e32 v88, v66, v88
	v_fma_f32 v88, v66, v88, v66
	v_mul_f32_e32 v88, 0xbfcc422a, v88
	v_mul_f32_e32 v88, 0x3fb8aa3b, v88
	v_exp_f32_e32 v88, v88
	v_cvt_pk_bf16_f32 v83, v84, v85
	s_nop 0
	v_add_f32_e32 v88, 1.0, v88
	v_rcp_f32_e32 v89, v88
	s_nop 0
	v_mul_f32_e32 v88, v66, v89
	v_mul_f32_e32 v89, 0x3d372713, v67
	v_mul_f32_e32 v89, v67, v89
	v_fma_f32 v89, v67, v89, v67
	v_mul_f32_e32 v89, 0xbfcc422a, v89
	v_mul_f32_e32 v89, 0x3fb8aa3b, v89
	v_exp_f32_e32 v89, v89
	s_nop 0
	v_add_f32_e32 v89, 1.0, v89
	v_rcp_f32_e32 v93, v89
	s_nop 0
	v_mul_f32_e32 v89, v67, v93
	v_mul_f32_e32 v93, 0x3d372713, v68
	v_mul_f32_e32 v93, v68, v93
	v_fma_f32 v93, v68, v93, v68
	v_mul_f32_e32 v93, 0xbfcc422a, v93
	v_mul_f32_e32 v93, 0x3fb8aa3b, v93
	v_exp_f32_e32 v93, v93
	v_cvt_pk_bf16_f32 v84, v88, v89
	v_lshl_add_u64 v[88:89], v[170:171], 0, s[42:43]
	v_readlane_b32 s43, v255, 41
	v_add_f32_e32 v93, 1.0, v93
	v_div_scale_f32 v94, s[12:13], v93, v93, v68
	v_rcp_f32_e32 v95, v94
	v_lshl_add_u64 v[86:87], v[88:89], 1, v[86:87]
	v_fma_f32 v96, -v94, v95, 1.0
	v_fmac_f32_e32 v95, v96, v95
	v_div_scale_f32 v96, vcc, v68, v93, v68
	v_mul_f32_e32 v97, v96, v95
	v_fma_f32 v99, -v94, v97, v96
	v_fmac_f32_e32 v97, v99, v95
	v_fma_f32 v94, -v94, v97, v96
	v_div_fmas_f32 v94, v94, v95, v97
	v_div_fixup_f32 v93, v94, v93, v68
	v_mul_f32_e32 v94, 0x3d372713, v69
	v_mul_f32_e32 v94, v69, v94
	v_fma_f32 v94, v69, v94, v69
	v_mul_f32_e32 v94, 0xbfcc422a, v94
	v_mul_f32_e32 v94, 0x3fb8aa3b, v94
	v_exp_f32_e32 v94, v94
	s_nop 0
	v_add_f32_e32 v94, 1.0, v94
	v_rcp_f32_e32 v95, v94
	s_nop 0
	v_mul_f32_e32 v94, v69, v95
	v_cvt_pk_bf16_f32 v85, v93, v94
	global_store_dwordx4 v[86:87], v[82:85], off offset:256

.LBB0_475:
	s_addk_i32 s64, 0x80
	v_or_b32_e32 v82, s64, v155
	v_bitop3_b32 v87, s64, v240, v155 bitop3:0xc8
	v_cmp_gt_i32_e64 s[8:9], s76, v82
	v_cmp_lt_i32_e64 s[10:11], s79, v82
	s_ashr_i32 s26, s64, 13
	v_cndmask_b32_e64 v86, v177, v87, s[8:9]
	s_and_b64 vcc, exec, s[6:7]
	s_mov_b64 s[12:13], -1
	s_cbranch_vccnz .LBB0_534
	v_add_u32_e32 v16, 0xffffc000, v82
	s_andn2_b64 vcc, exec, s[86:87]
	s_cbranch_vccnz .LBB0_506
	v_ashrrev_i32_e32 v83, 31, v82
	v_mov_b64_e32 v[66:67], s[14:15]
	s_movk_i32 s12, 0x60
	v_mad_i64_i32 v[72:73], s[12:13], v82, s12, v[66:67]
	v_lshlrev_b64 v[66:67], 10, v[82:83]
	v_lshl_add_u64 v[70:71], s[50:51], 0, v[66:67]
	v_cndmask_b32_e64 v66, 0, 1, s[44:45]
	v_cmp_ne_u32_e64 s[12:13], 1, v66
	s_andn2_b64 vcc, exec, s[44:45]
	s_mov_b64 s[52:53], -1
	s_cbranch_vccnz .LBB0_493
	s_andn2_b64 vcc, exec, s[46:47]
	s_cbranch_vccnz .LBB0_482
	s_movk_i32 s27, 0x918
	v_cmp_gt_i32_e32 vcc, s27, v170
	s_and_saveexec_b64 s[52:53], vcc
	s_cbranch_execz .LBB0_481
	v_mul_f32_e32 v68, 0xbfb8aa3b, v64
	v_mul_f32_e32 v69, 0xbfb8aa3b, v65
	v_exp_f32_e32 v68, v68
	v_exp_f32_e32 v69, v69
	v_mul_f32_e32 v66, 0xbfb8aa3b, v62
	v_mul_f32_e32 v67, 0xbfb8aa3b, v63
	v_exp_f32_e32 v66, v66
	v_pk_add_f32 v[68:69], v[68:69], 1.0 op_sel_hi:[1,0]
	v_exp_f32_e32 v67, v67
	v_div_scale_f32 v76, s[68:69], v69, v69, 1.0
	v_rcp_f32_e32 v77, v76
	v_pk_add_f32 v[66:67], v[66:67], 1.0 op_sel_hi:[1,0]
	v_mov_b32_e32 v171, v17
	v_lshl_add_u64 v[74:75], v[170:171], 2, v[72:73]
	v_fma_f32 v78, -v76, v77, 1.0
	v_fmac_f32_e32 v77, v78, v77
	v_div_scale_f32 v78, vcc, 1.0, v69, 1.0
	v_mul_f32_e32 v79, v78, v77
	v_fma_f32 v80, -v76, v79, v78
	v_fmac_f32_e32 v79, v80, v77
	v_fma_f32 v76, -v76, v79, v78
	v_div_fmas_f32 v76, v76, v77, v79
	v_div_fixup_f32 v69, v76, v69, 1.0
	v_rcp_f32_e32 v68, v68
	s_nop 0
	v_rcp_f32_e32 v67, v67
	s_nop 0
	v_div_scale_f32 v76, s[68:69], v66, v66, 1.0
	v_rcp_f32_e32 v77, v76
	s_nop 0
	v_fma_f32 v78, -v76, v77, 1.0
	v_fmac_f32_e32 v77, v78, v77
	v_div_scale_f32 v78, vcc, 1.0, v66, 1.0
	v_mul_f32_e32 v79, v78, v77
	v_fma_f32 v80, -v76, v79, v78
	v_fmac_f32_e32 v79, v80, v77
	v_fma_f32 v76, -v76, v79, v78
	v_div_fmas_f32 v76, v76, v77, v79
	v_mul_f32_e32 v78, 0xbfb8aa3b, v60
	v_mul_f32_e32 v79, 0xbfb8aa3b, v61
	v_exp_f32_e32 v78, v78
	v_exp_f32_e32 v79, v79
	v_div_fixup_f32 v66, v76, v66, 1.0
	v_mul_f32_e32 v76, 0xbfb8aa3b, v58
	v_mul_f32_e32 v77, 0xbfb8aa3b, v59
	v_pk_add_f32 v[78:79], v[78:79], 1.0 op_sel_hi:[1,0]
	v_exp_f32_e32 v76, v76
	v_div_scale_f32 v80, s[68:69], v79, v79, 1.0
	v_rcp_f32_e32 v81, v80
	v_exp_f32_e32 v77, v77
	v_fma_f32 v83, -v80, v81, 1.0
	v_fmac_f32_e32 v81, v83, v81
	v_div_scale_f32 v83, vcc, 1.0, v79, 1.0
	v_mul_f32_e32 v84, v83, v81
	v_fma_f32 v85, -v80, v84, v83
	v_fmac_f32_e32 v84, v85, v81
	v_fma_f32 v80, -v80, v84, v83
	v_div_fmas_f32 v80, v80, v81, v84
	v_div_fixup_f32 v79, v80, v79, 1.0
	v_div_scale_f32 v80, s[68:69], v78, v78, 1.0
	v_rcp_f32_e32 v81, v80
	v_pk_add_f32 v[76:77], v[76:77], 1.0 op_sel_hi:[1,0]
	v_fma_f32 v83, -v80, v81, 1.0
	v_fmac_f32_e32 v81, v83, v81
	v_div_scale_f32 v83, vcc, 1.0, v78, 1.0
	v_mul_f32_e32 v84, v83, v81
	v_fma_f32 v85, -v80, v84, v83
	v_fmac_f32_e32 v84, v85, v81
	v_fma_f32 v80, -v80, v84, v83
	v_div_fmas_f32 v80, v80, v81, v84
	v_div_fixup_f32 v78, v80, v78, 1.0
	v_rcp_f32_e32 v77, v77
	s_nop 0
	v_div_scale_f32 v80, s[68:69], v76, v76, 1.0
	v_rcp_f32_e32 v81, v80
	s_nop 0
	v_fma_f32 v83, -v80, v81, 1.0
	v_fmac_f32_e32 v81, v83, v81
	v_div_scale_f32 v83, vcc, 1.0, v76, 1.0
	v_mul_f32_e32 v84, v83, v81
	v_fma_f32 v85, -v80, v84, v83
	v_fmac_f32_e32 v84, v85, v81
	v_fma_f32 v80, -v80, v84, v83
	v_div_fmas_f32 v80, v80, v81, v84
	v_add_co_u32_e32 v74, vcc, 0x138fd000, v74
	v_div_fixup_f32 v76, v80, v76, 1.0
	s_nop 0
	v_addc_co_u32_e32 v75, vcc, 0, v75, vcc
	global_store_dwordx4 v[74:75], v[66:69], off offset:3072
	global_store_dwordx4 v[74:75], v[76:79], off offset:3088

.LBB0_482:
	s_andn2_b64 vcc, exec, s[52:53]
	s_cbranch_vccnz .LBB0_484
	v_mul_f32_e32 v67, 0x3d372713, v62
	v_mul_f32_e32 v67, v62, v67
	v_fma_f32 v67, v62, v67, v62
	v_mul_f32_e32 v67, 0xbfcc422a, v67
	v_mul_f32_e32 v67, 0x3fb8aa3b, v67
	v_exp_f32_e32 v67, v67
	v_add_u32_e32 v66, s42, v170
	v_add_f32_e32 v67, 1.0, v67
	v_rcp_f32_e32 v68, v67
	s_nop 0
	v_mul_f32_e32 v67, v62, v68
	v_mul_f32_e32 v68, 0x3d372713, v63
	v_mul_f32_e32 v68, v63, v68
	v_fma_f32 v68, v63, v68, v63
	v_mul_f32_e32 v68, 0xbfcc422a, v68
	v_mul_f32_e32 v68, 0x3fb8aa3b, v68
	v_exp_f32_e32 v68, v68
	s_nop 0
	v_add_f32_e32 v68, 1.0, v68
	v_rcp_f32_e32 v69, v68
	s_nop 0
	v_mul_f32_e32 v68, v63, v69
	v_mul_f32_e32 v69, 0x3d372713, v64
	v_mul_f32_e32 v69, v64, v69
	v_fma_f32 v69, v64, v69, v64
	v_mul_f32_e32 v69, 0xbfcc422a, v69
	v_mul_f32_e32 v69, 0x3fb8aa3b, v69
	v_exp_f32_e32 v69, v69
	s_nop 0
	v_add_f32_e32 v69, 1.0, v69
	v_rcp_f32_e32 v74, v69
	s_nop 0
	v_mul_f32_e32 v69, v64, v74
	v_mul_f32_e32 v74, 0x3d372713, v65
	v_mul_f32_e32 v74, v65, v74
	v_fma_f32 v74, v65, v74, v65
	v_mul_f32_e32 v74, 0xbfcc422a, v74
	v_mul_f32_e32 v74, 0x3fb8aa3b, v74
	v_exp_f32_e32 v74, v74
	s_nop 0
	v_add_f32_e32 v74, 1.0, v74
	v_rcp_f32_e32 v75, v74
	s_nop 0
	v_mul_f32_e32 v75, v65, v75
	v_mul_f32_e32 v74, 0x3d372713, v58
	v_mul_f32_e32 v74, v58, v74
	v_fma_f32 v74, v58, v74, v58
	v_mul_f32_e32 v74, 0xbfcc422a, v74
	v_mul_f32_e32 v74, 0x3fb8aa3b, v74
	v_exp_f32_e32 v74, v74
	s_nop 0
	v_add_f32_e32 v74, 1.0, v74
	v_rcp_f32_e32 v76, v74
	s_nop 0
	v_mul_f32_e32 v76, v58, v76
	v_mul_f32_e32 v74, 0x3d372713, v59
	v_mul_f32_e32 v74, v59, v74
	v_fma_f32 v74, v59, v74, v59
	v_mul_f32_e32 v74, 0xbfcc422a, v74
	v_mul_f32_e32 v74, 0x3fb8aa3b, v74
	v_exp_f32_e32 v74, v74
	s_nop 0
	v_add_f32_e32 v74, 1.0, v74
	v_rcp_f32_e32 v77, v74
	s_nop 0
	v_mul_f32_e32 v77, v59, v77
	v_mul_f32_e32 v74, 0x3d372713, v60
	v_mul_f32_e32 v74, v60, v74
	v_fma_f32 v74, v60, v74, v60
	v_mul_f32_e32 v74, 0xbfcc422a, v74
	v_mul_f32_e32 v74, 0x3fb8aa3b, v74
	v_exp_f32_e32 v74, v74
	s_nop 0
	v_add_f32_e32 v74, 1.0, v74
	v_rcp_f32_e32 v78, v74
	s_nop 0
	v_mul_f32_e32 v78, v60, v78
	v_mul_f32_e32 v74, 0x3d372713, v61
	v_mul_f32_e32 v74, v61, v74
	v_fma_f32 v74, v61, v74, v61
	v_mul_f32_e32 v74, 0xbfcc422a, v74
	v_mul_f32_e32 v74, 0x3fb8aa3b, v74
	v_exp_f32_e32 v74, v74
	s_nop 0
	v_add_f32_e32 v74, 1.0, v74
	v_rcp_f32_e32 v79, v74
	s_nop 0
	v_mul_f32_e32 v79, v61, v79
	v_cvt_pk_bf16_f32 v74, v67, v68
	v_ashrrev_i32_e32 v67, 31, v66
	v_lshl_add_u64 v[66:67], v[66:67], 1, v[70:71]
	v_cvt_pk_bf16_f32 v75, v69, v75
	v_cvt_pk_bf16_f32 v76, v76, v77
	v_cvt_pk_bf16_f32 v77, v78, v79
	global_store_dwordx4 v[66:67], v[74:77], off

.LBB0_486:
	s_andn2_b64 vcc, exec, s[46:47]
	s_cbranch_vccnz .LBB0_490
	v_or_b32_e32 v66, 0x80, v170
	s_movk_i32 s12, 0x918
	v_cmp_gt_i32_e32 vcc, s12, v66
	s_and_saveexec_b64 s[12:13], vcc
	s_cbranch_execz .LBB0_489
	v_mul_f32_e32 v68, 0xbfb8aa3b, v56
	v_mul_f32_e32 v69, 0xbfb8aa3b, v57
	v_exp_f32_e32 v68, v68
	v_exp_f32_e32 v69, v69
	v_mul_f32_e32 v66, 0xbfb8aa3b, v54
	v_mul_f32_e32 v67, 0xbfb8aa3b, v55
	v_exp_f32_e32 v66, v66
	v_pk_add_f32 v[68:69], v[68:69], 1.0 op_sel_hi:[1,0]
	v_exp_f32_e32 v67, v67
	v_div_scale_f32 v77, s[52:53], v69, v69, 1.0
	v_rcp_f32_e32 v78, v77
	v_pk_add_f32 v[66:67], v[66:67], 1.0 op_sel_hi:[1,0]
	v_mov_b32_e32 v171, v17
	v_lshl_add_u64 v[72:73], v[170:171], 2, v[72:73]
	v_fma_f32 v79, -v77, v78, 1.0
	v_fmac_f32_e32 v78, v79, v78
	v_div_scale_f32 v79, vcc, 1.0, v69, 1.0
	v_mul_f32_e32 v80, v79, v78
	v_fma_f32 v81, -v77, v80, v79
	v_fmac_f32_e32 v80, v81, v78
	v_fma_f32 v77, -v77, v80, v79
	v_div_fmas_f32 v77, v77, v78, v80
	v_div_fixup_f32 v69, v77, v69, 1.0
	v_rcp_f32_e32 v68, v68
	s_nop 0
	v_rcp_f32_e32 v67, v67
	s_nop 0
	v_rcp_f32_e32 v66, v66
	s_nop 0
	v_mul_f32_e32 v77, 0xbfb8aa3b, v50
	v_exp_f32_e32 v78, v77
	v_mul_f32_e32 v77, 0xbfb8aa3b, v51
	v_exp_f32_e32 v79, v77
	v_mul_f32_e32 v77, 0xbfb8aa3b, v52
	v_exp_f32_e32 v80, v77
	v_mul_f32_e32 v77, 0xbfb8aa3b, v53
	v_exp_f32_e32 v81, v77
	v_pk_add_f32 v[78:79], v[78:79], 1.0 op_sel_hi:[1,0]
	v_pk_add_f32 v[80:81], v[80:81], 1.0 op_sel_hi:[1,0]
	s_nop 0
	v_rcp_f32_e32 v81, v81
	s_nop 0
	v_rcp_f32_e32 v80, v80
	s_nop 0
	v_rcp_f32_e32 v79, v79
	s_nop 0
	v_div_scale_f32 v77, s[52:53], v78, v78, 1.0
	v_rcp_f32_e32 v83, v77
	s_nop 0
	v_fma_f32 v84, -v77, v83, 1.0
	v_fmac_f32_e32 v83, v84, v83
	v_div_scale_f32 v84, vcc, 1.0, v78, 1.0
	v_mul_f32_e32 v85, v84, v83
	v_fma_f32 v88, -v77, v85, v84
	v_fmac_f32_e32 v85, v88, v83
	v_fma_f32 v77, -v77, v85, v84
	v_div_fmas_f32 v77, v77, v83, v85
	v_add_co_u32_e32 v72, vcc, 0x138fd000, v72
	v_div_fixup_f32 v78, v77, v78, 1.0
	s_nop 0
	v_addc_co_u32_e32 v73, vcc, 0, v73, vcc
	global_store_dwordx4 v[72:73], v[66:69], off offset:3584
	global_store_dwordx4 v[72:73], v[78:81], off offset:3600

.LBB0_490:
	s_andn2_b64 vcc, exec, s[12:13]
	s_cbranch_vccnz .LBB0_492
	v_mul_f32_e32 v66, 0x3d372713, v54
	v_mul_f32_e32 v66, v54, v66
	v_fma_f32 v66, v54, v66, v54
	v_mul_f32_e32 v66, 0xbfcc422a, v66
	v_mul_f32_e32 v66, 0x3fb8aa3b, v66
	v_exp_f32_e32 v66, v66
	s_ashr_i32 s43, s42, 31
	v_ashrrev_i32_e32 v171, 31, v170
	v_add_f32_e32 v66, 1.0, v66
	v_rcp_f32_e32 v67, v66
	s_nop 0
	v_mul_f32_e32 v66, v54, v67
	v_mul_f32_e32 v67, 0x3d372713, v55
	v_mul_f32_e32 v67, v55, v67
	v_fma_f32 v67, v55, v67, v55
	v_mul_f32_e32 v67, 0xbfcc422a, v67
	v_mul_f32_e32 v67, 0x3fb8aa3b, v67
	v_exp_f32_e32 v67, v67
	s_nop 0
	v_add_f32_e32 v67, 1.0, v67
	v_rcp_f32_e32 v68, v67
	s_nop 0
	v_mul_f32_e32 v67, v55, v68
	v_mul_f32_e32 v68, 0x3d372713, v56
	v_mul_f32_e32 v68, v56, v68
	v_fma_f32 v68, v56, v68, v56
	v_mul_f32_e32 v68, 0xbfcc422a, v68
	v_mul_f32_e32 v68, 0x3fb8aa3b, v68
	v_exp_f32_e32 v68, v68
	v_cvt_pk_bf16_f32 v66, v66, v67
	s_nop 0
	v_add_f32_e32 v68, 1.0, v68
	v_rcp_f32_e32 v69, v68
	s_nop 0
	v_mul_f32_e32 v68, v56, v69
	v_mul_f32_e32 v69, 0x3d372713, v57
	v_mul_f32_e32 v69, v57, v69
	v_fma_f32 v69, v57, v69, v57
	v_mul_f32_e32 v69, 0xbfcc422a, v69
	v_mul_f32_e32 v69, 0x3fb8aa3b, v69
	v_exp_f32_e32 v69, v69
	s_nop 0
	v_add_f32_e32 v69, 1.0, v69
	v_rcp_f32_e32 v72, v69
	s_nop 0
	v_mul_f32_e32 v69, v57, v72
	v_mul_f32_e32 v72, 0x3d372713, v50
	v_mul_f32_e32 v72, v50, v72
	v_fma_f32 v72, v50, v72, v50
	v_mul_f32_e32 v72, 0xbfcc422a, v72
	v_mul_f32_e32 v72, 0x3fb8aa3b, v72
	v_exp_f32_e32 v72, v72
	v_cvt_pk_bf16_f32 v67, v68, v69
	s_nop 0
	v_add_f32_e32 v72, 1.0, v72
	v_rcp_f32_e32 v73, v72
	s_nop 0
	v_mul_f32_e32 v72, v50, v73
	v_mul_f32_e32 v73, 0x3d372713, v51
	v_mul_f32_e32 v73, v51, v73
	v_fma_f32 v73, v51, v73, v51
	v_mul_f32_e32 v73, 0xbfcc422a, v73
	v_mul_f32_e32 v73, 0x3fb8aa3b, v73
	v_exp_f32_e32 v73, v73
	s_nop 0
	v_add_f32_e32 v73, 1.0, v73
	v_rcp_f32_e32 v77, v73
	s_nop 0
	v_mul_f32_e32 v73, v51, v77
	v_mul_f32_e32 v77, 0x3d372713, v52
	v_mul_f32_e32 v77, v52, v77
	v_fma_f32 v77, v52, v77, v52
	v_mul_f32_e32 v77, 0xbfcc422a, v77
	v_mul_f32_e32 v77, 0x3fb8aa3b, v77
	v_exp_f32_e32 v77, v77
	v_cvt_pk_bf16_f32 v68, v72, v73
	v_lshl_add_u64 v[72:73], v[170:171], 0, s[42:43]
	v_readlane_b32 s43, v255, 41
	v_add_f32_e32 v77, 1.0, v77
	v_div_scale_f32 v78, s[12:13], v77, v77, v52
	v_rcp_f32_e32 v79, v78
	v_lshl_add_u64 v[70:71], v[72:73], 1, v[70:71]
	v_fma_f32 v80, -v78, v79, 1.0
	v_fmac_f32_e32 v79, v80, v79
	v_div_scale_f32 v80, vcc, v52, v77, v52
	v_mul_f32_e32 v81, v80, v79
	v_fma_f32 v83, -v78, v81, v80
	v_fmac_f32_e32 v81, v83, v79
	v_fma_f32 v78, -v78, v81, v80
	v_div_fmas_f32 v78, v78, v79, v81
	v_div_fixup_f32 v77, v78, v77, v52
	v_mul_f32_e32 v78, 0x3d372713, v53
	v_mul_f32_e32 v78, v53, v78
	v_fma_f32 v78, v53, v78, v53
	v_mul_f32_e32 v78, 0xbfcc422a, v78
	v_mul_f32_e32 v78, 0x3fb8aa3b, v78
	v_exp_f32_e32 v78, v78
	s_nop 0
	v_add_f32_e32 v78, 1.0, v78
	v_rcp_f32_e32 v79, v78
	s_nop 0
	v_mul_f32_e32 v78, v53, v79
	v_cvt_pk_bf16_f32 v69, v77, v78
	global_store_dwordx4 v[70:71], v[66:69], off offset:256

.LBB0_536:
	v_or_b32_e32 v66, s64, v185
	v_bitop3_b32 v71, s64, v241, v185 bitop3:0xc8
	v_cmp_gt_i32_e64 s[8:9], s76, v66
	v_cmp_lt_i32_e64 s[10:11], s79, v66
	s_and_b64 vcc, exec, s[6:7]
	v_cndmask_b32_e64 v70, v177, v71, s[8:9]
	s_mov_b64 s[12:13], -1
	s_cbranch_vccnz .LBB0_595
	v_add_u32_e32 v16, 0xffffc000, v66
	s_andn2_b64 vcc, exec, s[86:87]
	s_cbranch_vccnz .LBB0_567
	v_ashrrev_i32_e32 v67, 31, v66
	v_mov_b64_e32 v[50:51], s[14:15]
	s_movk_i32 s12, 0x60
	v_mad_i64_i32 v[56:57], s[12:13], v66, s12, v[50:51]
	v_lshlrev_b64 v[50:51], 10, v[66:67]
	v_lshl_add_u64 v[54:55], s[50:51], 0, v[50:51]
	v_cndmask_b32_e64 v50, 0, 1, s[44:45]
	v_cmp_ne_u32_e64 s[12:13], 1, v50
	s_andn2_b64 vcc, exec, s[44:45]
	s_mov_b64 s[52:53], -1
	s_cbranch_vccnz .LBB0_554
	s_andn2_b64 vcc, exec, s[46:47]
	s_cbranch_vccnz .LBB0_543
	s_movk_i32 s27, 0x918
	v_cmp_gt_i32_e32 vcc, s27, v170
	s_and_saveexec_b64 s[52:53], vcc
	s_cbranch_execz .LBB0_542
	v_mul_f32_e32 v52, 0xbfb8aa3b, v48
	v_mul_f32_e32 v53, 0xbfb8aa3b, v49
	v_exp_f32_e32 v52, v52
	v_exp_f32_e32 v53, v53
	v_mul_f32_e32 v50, 0xbfb8aa3b, v46
	v_mul_f32_e32 v51, 0xbfb8aa3b, v47
	v_exp_f32_e32 v50, v50
	v_pk_add_f32 v[52:53], v[52:53], 1.0 op_sel_hi:[1,0]
	v_exp_f32_e32 v51, v51
	v_div_scale_f32 v60, s[68:69], v53, v53, 1.0
	v_rcp_f32_e32 v61, v60
	v_pk_add_f32 v[50:51], v[50:51], 1.0 op_sel_hi:[1,0]
	v_mov_b32_e32 v171, v17
	v_lshl_add_u64 v[58:59], v[170:171], 2, v[56:57]
	v_fma_f32 v62, -v60, v61, 1.0
	v_fmac_f32_e32 v61, v62, v61
	v_div_scale_f32 v62, vcc, 1.0, v53, 1.0
	v_mul_f32_e32 v63, v62, v61
	v_fma_f32 v64, -v60, v63, v62
	v_fmac_f32_e32 v63, v64, v61
	v_fma_f32 v60, -v60, v63, v62
	v_div_fmas_f32 v60, v60, v61, v63
	v_div_fixup_f32 v53, v60, v53, 1.0
	v_rcp_f32_e32 v52, v52
	s_nop 0
	v_rcp_f32_e32 v51, v51
	s_nop 0
	v_div_scale_f32 v60, s[68:69], v50, v50, 1.0
	v_rcp_f32_e32 v61, v60
	s_nop 0
	v_fma_f32 v62, -v60, v61, 1.0
	v_fmac_f32_e32 v61, v62, v61
	v_div_scale_f32 v62, vcc, 1.0, v50, 1.0
	v_mul_f32_e32 v63, v62, v61
	v_fma_f32 v64, -v60, v63, v62
	v_fmac_f32_e32 v63, v64, v61
	v_fma_f32 v60, -v60, v63, v62
	v_div_fmas_f32 v60, v60, v61, v63
	v_mul_f32_e32 v62, 0xbfb8aa3b, v44
	v_mul_f32_e32 v63, 0xbfb8aa3b, v45
	v_exp_f32_e32 v62, v62
	v_exp_f32_e32 v63, v63
	v_div_fixup_f32 v50, v60, v50, 1.0
	v_mul_f32_e32 v60, 0xbfb8aa3b, v42
	v_mul_f32_e32 v61, 0xbfb8aa3b, v43
	v_pk_add_f32 v[62:63], v[62:63], 1.0 op_sel_hi:[1,0]
	v_exp_f32_e32 v60, v60
	v_div_scale_f32 v64, s[68:69], v63, v63, 1.0
	v_rcp_f32_e32 v65, v64
	v_exp_f32_e32 v61, v61
	v_fma_f32 v67, -v64, v65, 1.0
	v_fmac_f32_e32 v65, v67, v65
	v_div_scale_f32 v67, vcc, 1.0, v63, 1.0
	v_mul_f32_e32 v68, v67, v65
	v_fma_f32 v69, -v64, v68, v67
	v_fmac_f32_e32 v68, v69, v65
	v_fma_f32 v64, -v64, v68, v67
	v_div_fmas_f32 v64, v64, v65, v68
	v_div_fixup_f32 v63, v64, v63, 1.0
	v_div_scale_f32 v64, s[68:69], v62, v62, 1.0
	v_rcp_f32_e32 v65, v64
	v_pk_add_f32 v[60:61], v[60:61], 1.0 op_sel_hi:[1,0]
	v_fma_f32 v67, -v64, v65, 1.0
	v_fmac_f32_e32 v65, v67, v65
	v_div_scale_f32 v67, vcc, 1.0, v62, 1.0
	v_mul_f32_e32 v68, v67, v65
	v_fma_f32 v69, -v64, v68, v67
	v_fmac_f32_e32 v68, v69, v65
	v_fma_f32 v64, -v64, v68, v67
	v_div_fmas_f32 v64, v64, v65, v68
	v_div_fixup_f32 v62, v64, v62, 1.0
	v_rcp_f32_e32 v61, v61
	s_nop 0
	v_div_scale_f32 v64, s[68:69], v60, v60, 1.0
	v_rcp_f32_e32 v65, v64
	s_nop 0
	v_fma_f32 v67, -v64, v65, 1.0
	v_fmac_f32_e32 v65, v67, v65
	v_div_scale_f32 v67, vcc, 1.0, v60, 1.0
	v_mul_f32_e32 v68, v67, v65
	v_fma_f32 v69, -v64, v68, v67
	v_fmac_f32_e32 v68, v69, v65
	v_fma_f32 v64, -v64, v68, v67
	v_div_fmas_f32 v64, v64, v65, v68
	v_add_co_u32_e32 v58, vcc, 0x138fd000, v58
	v_div_fixup_f32 v60, v64, v60, 1.0
	s_nop 0
	v_addc_co_u32_e32 v59, vcc, 0, v59, vcc
	global_store_dwordx4 v[58:59], v[50:53], off offset:3072
	global_store_dwordx4 v[58:59], v[60:63], off offset:3088

.LBB0_543:
	s_andn2_b64 vcc, exec, s[52:53]
	s_cbranch_vccnz .LBB0_545
	v_mul_f32_e32 v51, 0x3d372713, v46
	v_mul_f32_e32 v51, v46, v51
	v_fma_f32 v51, v46, v51, v46
	v_mul_f32_e32 v51, 0xbfcc422a, v51
	v_mul_f32_e32 v51, 0x3fb8aa3b, v51
	v_exp_f32_e32 v51, v51
	v_add_u32_e32 v50, s42, v170
	v_add_f32_e32 v51, 1.0, v51
	v_rcp_f32_e32 v52, v51
	s_nop 0
	v_mul_f32_e32 v51, v46, v52
	v_mul_f32_e32 v52, 0x3d372713, v47
	v_mul_f32_e32 v52, v47, v52
	v_fma_f32 v52, v47, v52, v47
	v_mul_f32_e32 v52, 0xbfcc422a, v52
	v_mul_f32_e32 v52, 0x3fb8aa3b, v52
	v_exp_f32_e32 v52, v52
	s_nop 0
	v_add_f32_e32 v52, 1.0, v52
	v_rcp_f32_e32 v53, v52
	s_nop 0
	v_mul_f32_e32 v52, v47, v53
	v_mul_f32_e32 v53, 0x3d372713, v48
	v_mul_f32_e32 v53, v48, v53
	v_fma_f32 v53, v48, v53, v48
	v_mul_f32_e32 v53, 0xbfcc422a, v53
	v_mul_f32_e32 v53, 0x3fb8aa3b, v53
	v_exp_f32_e32 v53, v53
	s_nop 0
	v_add_f32_e32 v53, 1.0, v53
	v_rcp_f32_e32 v58, v53
	s_nop 0
	v_mul_f32_e32 v53, v48, v58
	v_mul_f32_e32 v58, 0x3d372713, v49
	v_mul_f32_e32 v58, v49, v58
	v_fma_f32 v58, v49, v58, v49
	v_mul_f32_e32 v58, 0xbfcc422a, v58
	v_mul_f32_e32 v58, 0x3fb8aa3b, v58
	v_exp_f32_e32 v58, v58
	s_nop 0
	v_add_f32_e32 v58, 1.0, v58
	v_rcp_f32_e32 v59, v58
	s_nop 0
	v_mul_f32_e32 v59, v49, v59
	v_mul_f32_e32 v58, 0x3d372713, v42
	v_mul_f32_e32 v58, v42, v58
	v_fma_f32 v58, v42, v58, v42
	v_mul_f32_e32 v58, 0xbfcc422a, v58
	v_mul_f32_e32 v58, 0x3fb8aa3b, v58
	v_exp_f32_e32 v58, v58
	s_nop 0
	v_add_f32_e32 v58, 1.0, v58
	v_rcp_f32_e32 v60, v58
	s_nop 0
	v_mul_f32_e32 v60, v42, v60
	v_mul_f32_e32 v58, 0x3d372713, v43
	v_mul_f32_e32 v58, v43, v58
	v_fma_f32 v58, v43, v58, v43
	v_mul_f32_e32 v58, 0xbfcc422a, v58
	v_mul_f32_e32 v58, 0x3fb8aa3b, v58
	v_exp_f32_e32 v58, v58
	s_nop 0
	v_add_f32_e32 v58, 1.0, v58
	v_rcp_f32_e32 v61, v58
	s_nop 0
	v_mul_f32_e32 v61, v43, v61
	v_mul_f32_e32 v58, 0x3d372713, v44
	v_mul_f32_e32 v58, v44, v58
	v_fma_f32 v58, v44, v58, v44
	v_mul_f32_e32 v58, 0xbfcc422a, v58
	v_mul_f32_e32 v58, 0x3fb8aa3b, v58
	v_exp_f32_e32 v58, v58
	s_nop 0
	v_add_f32_e32 v58, 1.0, v58
	v_rcp_f32_e32 v62, v58
	s_nop 0
	v_mul_f32_e32 v62, v44, v62
	v_mul_f32_e32 v58, 0x3d372713, v45
	v_mul_f32_e32 v58, v45, v58
	v_fma_f32 v58, v45, v58, v45
	v_mul_f32_e32 v58, 0xbfcc422a, v58
	v_mul_f32_e32 v58, 0x3fb8aa3b, v58
	v_exp_f32_e32 v58, v58
	s_nop 0
	v_add_f32_e32 v58, 1.0, v58
	v_rcp_f32_e32 v63, v58
	s_nop 0
	v_mul_f32_e32 v63, v45, v63
	v_cvt_pk_bf16_f32 v58, v51, v52
	v_ashrrev_i32_e32 v51, 31, v50
	v_lshl_add_u64 v[50:51], v[50:51], 1, v[54:55]
	v_cvt_pk_bf16_f32 v59, v53, v59
	v_cvt_pk_bf16_f32 v60, v60, v61
	v_cvt_pk_bf16_f32 v61, v62, v63
	global_store_dwordx4 v[50:51], v[58:61], off

.LBB0_547:
	s_andn2_b64 vcc, exec, s[46:47]
	s_cbranch_vccnz .LBB0_551
	v_or_b32_e32 v50, 0x80, v170
	s_movk_i32 s12, 0x918
	v_cmp_gt_i32_e32 vcc, s12, v50
	s_and_saveexec_b64 s[12:13], vcc
	s_cbranch_execz .LBB0_550
	v_mul_f32_e32 v52, 0xbfb8aa3b, v40
	v_mul_f32_e32 v53, 0xbfb8aa3b, v41
	v_exp_f32_e32 v52, v52
	v_exp_f32_e32 v53, v53
	v_mul_f32_e32 v50, 0xbfb8aa3b, v38
	v_mul_f32_e32 v51, 0xbfb8aa3b, v39
	v_exp_f32_e32 v50, v50
	v_pk_add_f32 v[52:53], v[52:53], 1.0 op_sel_hi:[1,0]
	v_exp_f32_e32 v51, v51
	v_div_scale_f32 v61, s[52:53], v53, v53, 1.0
	v_rcp_f32_e32 v62, v61
	v_pk_add_f32 v[50:51], v[50:51], 1.0 op_sel_hi:[1,0]
	v_mov_b32_e32 v171, v17
	v_lshl_add_u64 v[56:57], v[170:171], 2, v[56:57]
	v_fma_f32 v63, -v61, v62, 1.0
	v_fmac_f32_e32 v62, v63, v62
	v_div_scale_f32 v63, vcc, 1.0, v53, 1.0
	v_mul_f32_e32 v64, v63, v62
	v_fma_f32 v65, -v61, v64, v63
	v_fmac_f32_e32 v64, v65, v62
	v_fma_f32 v61, -v61, v64, v63
	v_div_fmas_f32 v61, v61, v62, v64
	v_div_fixup_f32 v53, v61, v53, 1.0
	v_rcp_f32_e32 v52, v52
	s_nop 0
	v_rcp_f32_e32 v51, v51
	s_nop 0
	v_rcp_f32_e32 v50, v50
	s_nop 0
	v_mul_f32_e32 v61, 0xbfb8aa3b, v34
	v_exp_f32_e32 v62, v61
	v_mul_f32_e32 v61, 0xbfb8aa3b, v35
	v_exp_f32_e32 v63, v61
	v_mul_f32_e32 v61, 0xbfb8aa3b, v36
	v_exp_f32_e32 v64, v61
	v_mul_f32_e32 v61, 0xbfb8aa3b, v37
	v_exp_f32_e32 v65, v61
	v_pk_add_f32 v[62:63], v[62:63], 1.0 op_sel_hi:[1,0]
	v_pk_add_f32 v[64:65], v[64:65], 1.0 op_sel_hi:[1,0]
	s_nop 0
	v_rcp_f32_e32 v65, v65
	s_nop 0
	v_rcp_f32_e32 v64, v64
	s_nop 0
	v_rcp_f32_e32 v63, v63
	s_nop 0
	v_div_scale_f32 v61, s[52:53], v62, v62, 1.0
	v_rcp_f32_e32 v67, v61
	s_nop 0
	v_fma_f32 v68, -v61, v67, 1.0
	v_fmac_f32_e32 v67, v68, v67
	v_div_scale_f32 v68, vcc, 1.0, v62, 1.0
	v_mul_f32_e32 v69, v68, v67
	v_fma_f32 v72, -v61, v69, v68
	v_fmac_f32_e32 v69, v72, v67
	v_fma_f32 v61, -v61, v69, v68
	v_div_fmas_f32 v61, v61, v67, v69
	v_add_co_u32_e32 v56, vcc, 0x138fd000, v56
	v_div_fixup_f32 v62, v61, v62, 1.0
	s_nop 0
	v_addc_co_u32_e32 v57, vcc, 0, v57, vcc
	global_store_dwordx4 v[56:57], v[50:53], off offset:3584
	global_store_dwordx4 v[56:57], v[62:65], off offset:3600

.LBB0_551:
	s_andn2_b64 vcc, exec, s[12:13]
	s_cbranch_vccnz .LBB0_553
	v_mul_f32_e32 v50, 0x3d372713, v38
	v_mul_f32_e32 v50, v38, v50
	v_fma_f32 v50, v38, v50, v38
	v_mul_f32_e32 v50, 0xbfcc422a, v50
	v_mul_f32_e32 v50, 0x3fb8aa3b, v50
	v_exp_f32_e32 v50, v50
	s_ashr_i32 s43, s42, 31
	v_ashrrev_i32_e32 v171, 31, v170
	v_add_f32_e32 v50, 1.0, v50
	v_rcp_f32_e32 v51, v50
	s_nop 0
	v_mul_f32_e32 v50, v38, v51
	v_mul_f32_e32 v51, 0x3d372713, v39
	v_mul_f32_e32 v51, v39, v51
	v_fma_f32 v51, v39, v51, v39
	v_mul_f32_e32 v51, 0xbfcc422a, v51
	v_mul_f32_e32 v51, 0x3fb8aa3b, v51
	v_exp_f32_e32 v51, v51
	s_nop 0
	v_add_f32_e32 v51, 1.0, v51
	v_rcp_f32_e32 v52, v51
	s_nop 0
	v_mul_f32_e32 v51, v39, v52
	v_mul_f32_e32 v52, 0x3d372713, v40
	v_mul_f32_e32 v52, v40, v52
	v_fma_f32 v52, v40, v52, v40
	v_mul_f32_e32 v52, 0xbfcc422a, v52
	v_mul_f32_e32 v52, 0x3fb8aa3b, v52
	v_exp_f32_e32 v52, v52
	v_cvt_pk_bf16_f32 v50, v50, v51
	s_nop 0
	v_add_f32_e32 v52, 1.0, v52
	v_rcp_f32_e32 v53, v52
	s_nop 0
	v_mul_f32_e32 v52, v40, v53
	v_mul_f32_e32 v53, 0x3d372713, v41
	v_mul_f32_e32 v53, v41, v53
	v_fma_f32 v53, v41, v53, v41
	v_mul_f32_e32 v53, 0xbfcc422a, v53
	v_mul_f32_e32 v53, 0x3fb8aa3b, v53
	v_exp_f32_e32 v53, v53
	s_nop 0
	v_add_f32_e32 v53, 1.0, v53
	v_rcp_f32_e32 v56, v53
	s_nop 0
	v_mul_f32_e32 v53, v41, v56
	v_mul_f32_e32 v56, 0x3d372713, v34
	v_mul_f32_e32 v56, v34, v56
	v_fma_f32 v56, v34, v56, v34
	v_mul_f32_e32 v56, 0xbfcc422a, v56
	v_mul_f32_e32 v56, 0x3fb8aa3b, v56
	v_exp_f32_e32 v56, v56
	v_cvt_pk_bf16_f32 v51, v52, v53
	s_nop 0
	v_add_f32_e32 v56, 1.0, v56
	v_rcp_f32_e32 v57, v56
	s_nop 0
	v_mul_f32_e32 v56, v34, v57
	v_mul_f32_e32 v57, 0x3d372713, v35
	v_mul_f32_e32 v57, v35, v57
	v_fma_f32 v57, v35, v57, v35
	v_mul_f32_e32 v57, 0xbfcc422a, v57
	v_mul_f32_e32 v57, 0x3fb8aa3b, v57
	v_exp_f32_e32 v57, v57
	s_nop 0
	v_add_f32_e32 v57, 1.0, v57
	v_rcp_f32_e32 v61, v57
	s_nop 0
	v_mul_f32_e32 v57, v35, v61
	v_mul_f32_e32 v61, 0x3d372713, v36
	v_mul_f32_e32 v61, v36, v61
	v_fma_f32 v61, v36, v61, v36
	v_mul_f32_e32 v61, 0xbfcc422a, v61
	v_mul_f32_e32 v61, 0x3fb8aa3b, v61
	v_exp_f32_e32 v61, v61
	v_cvt_pk_bf16_f32 v52, v56, v57
	v_lshl_add_u64 v[56:57], v[170:171], 0, s[42:43]
	v_readlane_b32 s43, v255, 41
	v_add_f32_e32 v61, 1.0, v61
	v_div_scale_f32 v62, s[12:13], v61, v61, v36
	v_rcp_f32_e32 v63, v62
	v_lshl_add_u64 v[54:55], v[56:57], 1, v[54:55]
	v_fma_f32 v64, -v62, v63, 1.0
	v_fmac_f32_e32 v63, v64, v63
	v_div_scale_f32 v64, vcc, v36, v61, v36
	v_mul_f32_e32 v65, v64, v63
	v_fma_f32 v67, -v62, v65, v64
	v_fmac_f32_e32 v65, v67, v63
	v_fma_f32 v62, -v62, v65, v64
	v_div_fmas_f32 v62, v62, v63, v65
	v_div_fixup_f32 v61, v62, v61, v36
	v_mul_f32_e32 v62, 0x3d372713, v37
	v_mul_f32_e32 v62, v37, v62
	v_fma_f32 v62, v37, v62, v37
	v_mul_f32_e32 v62, 0xbfcc422a, v62
	v_mul_f32_e32 v62, 0x3fb8aa3b, v62
	v_exp_f32_e32 v62, v62
	s_nop 0
	v_add_f32_e32 v62, 1.0, v62
	v_rcp_f32_e32 v63, v62
	s_nop 0
	v_mul_f32_e32 v62, v37, v63
	v_cvt_pk_bf16_f32 v53, v61, v62
	global_store_dwordx4 v[54:55], v[50:53], off offset:256

.LBB0_597:
	v_or_b32_e32 v50, s64, v186
	v_bitop3_b32 v55, s64, v242, v186 bitop3:0xc8
	v_cmp_gt_i32_e64 s[8:9], s76, v50
	v_cmp_lt_i32_e64 s[10:11], s79, v50
	s_and_b64 vcc, exec, s[6:7]
	v_cndmask_b32_e64 v54, v177, v55, s[8:9]
	s_mov_b64 s[12:13], -1
	s_cbranch_vccnz .LBB0_656
	v_add_u32_e32 v16, 0xffffc000, v50
	s_andn2_b64 vcc, exec, s[86:87]
	s_cbranch_vccnz .LBB0_628
	v_ashrrev_i32_e32 v51, 31, v50
	v_mov_b64_e32 v[34:35], s[14:15]
	s_movk_i32 s12, 0x60
	v_mad_i64_i32 v[40:41], s[12:13], v50, s12, v[34:35]
	v_lshlrev_b64 v[34:35], 10, v[50:51]
	v_lshl_add_u64 v[38:39], s[50:51], 0, v[34:35]
	v_cndmask_b32_e64 v34, 0, 1, s[44:45]
	v_cmp_ne_u32_e64 s[12:13], 1, v34
	s_andn2_b64 vcc, exec, s[44:45]
	s_mov_b64 s[52:53], -1
	s_cbranch_vccnz .LBB0_615
	s_andn2_b64 vcc, exec, s[46:47]
	s_cbranch_vccnz .LBB0_604
	s_movk_i32 s27, 0x918
	v_cmp_gt_i32_e32 vcc, s27, v170
	s_and_saveexec_b64 s[52:53], vcc
	s_cbranch_execz .LBB0_603
	v_mul_f32_e32 v36, 0xbfb8aa3b, v32
	v_mul_f32_e32 v37, 0xbfb8aa3b, v33
	v_exp_f32_e32 v36, v36
	v_exp_f32_e32 v37, v37
	v_mul_f32_e32 v34, 0xbfb8aa3b, v30
	v_mul_f32_e32 v35, 0xbfb8aa3b, v31
	v_exp_f32_e32 v34, v34
	v_pk_add_f32 v[36:37], v[36:37], 1.0 op_sel_hi:[1,0]
	v_exp_f32_e32 v35, v35
	v_div_scale_f32 v44, s[68:69], v37, v37, 1.0
	v_rcp_f32_e32 v45, v44
	v_pk_add_f32 v[34:35], v[34:35], 1.0 op_sel_hi:[1,0]
	v_mov_b32_e32 v171, v17
	v_lshl_add_u64 v[42:43], v[170:171], 2, v[40:41]
	v_fma_f32 v46, -v44, v45, 1.0
	v_fmac_f32_e32 v45, v46, v45
	v_div_scale_f32 v46, vcc, 1.0, v37, 1.0
	v_mul_f32_e32 v47, v46, v45
	v_fma_f32 v48, -v44, v47, v46
	v_fmac_f32_e32 v47, v48, v45
	v_fma_f32 v44, -v44, v47, v46
	v_div_fmas_f32 v44, v44, v45, v47
	v_div_fixup_f32 v37, v44, v37, 1.0
	v_rcp_f32_e32 v36, v36
	s_nop 0
	v_rcp_f32_e32 v35, v35
	s_nop 0
	v_div_scale_f32 v44, s[68:69], v34, v34, 1.0
	v_rcp_f32_e32 v45, v44
	s_nop 0
	v_fma_f32 v46, -v44, v45, 1.0
	v_fmac_f32_e32 v45, v46, v45
	v_div_scale_f32 v46, vcc, 1.0, v34, 1.0
	v_mul_f32_e32 v47, v46, v45
	v_fma_f32 v48, -v44, v47, v46
	v_fmac_f32_e32 v47, v48, v45
	v_fma_f32 v44, -v44, v47, v46
	v_div_fmas_f32 v44, v44, v45, v47
	v_mul_f32_e32 v46, 0xbfb8aa3b, v28
	v_mul_f32_e32 v47, 0xbfb8aa3b, v29
	v_exp_f32_e32 v46, v46
	v_exp_f32_e32 v47, v47
	v_div_fixup_f32 v34, v44, v34, 1.0
	v_mul_f32_e32 v44, 0xbfb8aa3b, v26
	v_mul_f32_e32 v45, 0xbfb8aa3b, v27
	v_pk_add_f32 v[46:47], v[46:47], 1.0 op_sel_hi:[1,0]
	v_exp_f32_e32 v44, v44
	v_div_scale_f32 v48, s[68:69], v47, v47, 1.0
	v_rcp_f32_e32 v49, v48
	v_exp_f32_e32 v45, v45
	v_fma_f32 v51, -v48, v49, 1.0
	v_fmac_f32_e32 v49, v51, v49
	v_div_scale_f32 v51, vcc, 1.0, v47, 1.0
	v_mul_f32_e32 v52, v51, v49
	v_fma_f32 v53, -v48, v52, v51
	v_fmac_f32_e32 v52, v53, v49
	v_fma_f32 v48, -v48, v52, v51
	v_div_fmas_f32 v48, v48, v49, v52
	v_div_fixup_f32 v47, v48, v47, 1.0
	v_div_scale_f32 v48, s[68:69], v46, v46, 1.0
	v_rcp_f32_e32 v49, v48
	v_pk_add_f32 v[44:45], v[44:45], 1.0 op_sel_hi:[1,0]
	v_fma_f32 v51, -v48, v49, 1.0
	v_fmac_f32_e32 v49, v51, v49
	v_div_scale_f32 v51, vcc, 1.0, v46, 1.0
	v_mul_f32_e32 v52, v51, v49
	v_fma_f32 v53, -v48, v52, v51
	v_fmac_f32_e32 v52, v53, v49
	v_fma_f32 v48, -v48, v52, v51
	v_div_fmas_f32 v48, v48, v49, v52
	v_div_fixup_f32 v46, v48, v46, 1.0
	v_rcp_f32_e32 v45, v45
	s_nop 0
	v_div_scale_f32 v48, s[68:69], v44, v44, 1.0
	v_rcp_f32_e32 v49, v48
	s_nop 0
	v_fma_f32 v51, -v48, v49, 1.0
	v_fmac_f32_e32 v49, v51, v49
	v_div_scale_f32 v51, vcc, 1.0, v44, 1.0
	v_mul_f32_e32 v52, v51, v49
	v_fma_f32 v53, -v48, v52, v51
	v_fmac_f32_e32 v52, v53, v49
	v_fma_f32 v48, -v48, v52, v51
	v_div_fmas_f32 v48, v48, v49, v52
	v_add_co_u32_e32 v42, vcc, 0x138fd000, v42
	v_div_fixup_f32 v44, v48, v44, 1.0
	s_nop 0
	v_addc_co_u32_e32 v43, vcc, 0, v43, vcc
	global_store_dwordx4 v[42:43], v[34:37], off offset:3072
	global_store_dwordx4 v[42:43], v[44:47], off offset:3088

.LBB0_604:
	s_andn2_b64 vcc, exec, s[52:53]
	s_cbranch_vccnz .LBB0_606
	v_mul_f32_e32 v35, 0x3d372713, v30
	v_mul_f32_e32 v35, v30, v35
	v_fma_f32 v35, v30, v35, v30
	v_mul_f32_e32 v35, 0xbfcc422a, v35
	v_mul_f32_e32 v35, 0x3fb8aa3b, v35
	v_exp_f32_e32 v35, v35
	v_add_u32_e32 v34, s42, v170
	v_add_f32_e32 v35, 1.0, v35
	v_rcp_f32_e32 v36, v35
	s_nop 0
	v_mul_f32_e32 v35, v30, v36
	v_mul_f32_e32 v36, 0x3d372713, v31
	v_mul_f32_e32 v36, v31, v36
	v_fma_f32 v36, v31, v36, v31
	v_mul_f32_e32 v36, 0xbfcc422a, v36
	v_mul_f32_e32 v36, 0x3fb8aa3b, v36
	v_exp_f32_e32 v36, v36
	s_nop 0
	v_add_f32_e32 v36, 1.0, v36
	v_rcp_f32_e32 v37, v36
	s_nop 0
	v_mul_f32_e32 v36, v31, v37
	v_mul_f32_e32 v37, 0x3d372713, v32
	v_mul_f32_e32 v37, v32, v37
	v_fma_f32 v37, v32, v37, v32
	v_mul_f32_e32 v37, 0xbfcc422a, v37
	v_mul_f32_e32 v37, 0x3fb8aa3b, v37
	v_exp_f32_e32 v37, v37
	s_nop 0
	v_add_f32_e32 v37, 1.0, v37
	v_rcp_f32_e32 v42, v37
	s_nop 0
	v_mul_f32_e32 v37, v32, v42
	v_mul_f32_e32 v42, 0x3d372713, v33
	v_mul_f32_e32 v42, v33, v42
	v_fma_f32 v42, v33, v42, v33
	v_mul_f32_e32 v42, 0xbfcc422a, v42
	v_mul_f32_e32 v42, 0x3fb8aa3b, v42
	v_exp_f32_e32 v42, v42
	s_nop 0
	v_add_f32_e32 v42, 1.0, v42
	v_rcp_f32_e32 v43, v42
	s_nop 0
	v_mul_f32_e32 v43, v33, v43
	v_mul_f32_e32 v42, 0x3d372713, v26
	v_mul_f32_e32 v42, v26, v42
	v_fma_f32 v42, v26, v42, v26
	v_mul_f32_e32 v42, 0xbfcc422a, v42
	v_mul_f32_e32 v42, 0x3fb8aa3b, v42
	v_exp_f32_e32 v42, v42
	s_nop 0
	v_add_f32_e32 v42, 1.0, v42
	v_rcp_f32_e32 v44, v42
	s_nop 0
	v_mul_f32_e32 v44, v26, v44
	v_mul_f32_e32 v42, 0x3d372713, v27
	v_mul_f32_e32 v42, v27, v42
	v_fma_f32 v42, v27, v42, v27
	v_mul_f32_e32 v42, 0xbfcc422a, v42
	v_mul_f32_e32 v42, 0x3fb8aa3b, v42
	v_exp_f32_e32 v42, v42
	s_nop 0
	v_add_f32_e32 v42, 1.0, v42
	v_rcp_f32_e32 v45, v42
	s_nop 0
	v_mul_f32_e32 v45, v27, v45
	v_mul_f32_e32 v42, 0x3d372713, v28
	v_mul_f32_e32 v42, v28, v42
	v_fma_f32 v42, v28, v42, v28
	v_mul_f32_e32 v42, 0xbfcc422a, v42
	v_mul_f32_e32 v42, 0x3fb8aa3b, v42
	v_exp_f32_e32 v42, v42
	s_nop 0
	v_add_f32_e32 v42, 1.0, v42
	v_rcp_f32_e32 v46, v42
	s_nop 0
	v_mul_f32_e32 v46, v28, v46
	v_mul_f32_e32 v42, 0x3d372713, v29
	v_mul_f32_e32 v42, v29, v42
	v_fma_f32 v42, v29, v42, v29
	v_mul_f32_e32 v42, 0xbfcc422a, v42
	v_mul_f32_e32 v42, 0x3fb8aa3b, v42
	v_exp_f32_e32 v42, v42
	s_nop 0
	v_add_f32_e32 v42, 1.0, v42
	v_rcp_f32_e32 v47, v42
	s_nop 0
	v_mul_f32_e32 v47, v29, v47
	v_cvt_pk_bf16_f32 v42, v35, v36
	v_ashrrev_i32_e32 v35, 31, v34
	v_lshl_add_u64 v[34:35], v[34:35], 1, v[38:39]
	v_cvt_pk_bf16_f32 v43, v37, v43
	v_cvt_pk_bf16_f32 v44, v44, v45
	v_cvt_pk_bf16_f32 v45, v46, v47
	global_store_dwordx4 v[34:35], v[42:45], off

.LBB0_608:
	s_andn2_b64 vcc, exec, s[46:47]
	s_cbranch_vccnz .LBB0_612
	v_or_b32_e32 v34, 0x80, v170
	s_movk_i32 s12, 0x918
	v_cmp_gt_i32_e32 vcc, s12, v34
	s_and_saveexec_b64 s[12:13], vcc
	s_cbranch_execz .LBB0_611
	v_mul_f32_e32 v36, 0xbfb8aa3b, v24
	v_mul_f32_e32 v37, 0xbfb8aa3b, v25
	v_exp_f32_e32 v36, v36
	v_exp_f32_e32 v37, v37
	v_mul_f32_e32 v34, 0xbfb8aa3b, v22
	v_mul_f32_e32 v35, 0xbfb8aa3b, v23
	v_exp_f32_e32 v34, v34
	v_pk_add_f32 v[36:37], v[36:37], 1.0 op_sel_hi:[1,0]
	v_exp_f32_e32 v35, v35
	v_div_scale_f32 v45, s[52:53], v37, v37, 1.0
	v_rcp_f32_e32 v46, v45
	v_pk_add_f32 v[34:35], v[34:35], 1.0 op_sel_hi:[1,0]
	v_mov_b32_e32 v171, v17
	v_lshl_add_u64 v[40:41], v[170:171], 2, v[40:41]
	v_fma_f32 v47, -v45, v46, 1.0
	v_fmac_f32_e32 v46, v47, v46
	v_div_scale_f32 v47, vcc, 1.0, v37, 1.0
	v_mul_f32_e32 v48, v47, v46
	v_fma_f32 v49, -v45, v48, v47
	v_fmac_f32_e32 v48, v49, v46
	v_fma_f32 v45, -v45, v48, v47
	v_div_fmas_f32 v45, v45, v46, v48
	v_div_fixup_f32 v37, v45, v37, 1.0
	v_rcp_f32_e32 v36, v36
	s_nop 0
	v_rcp_f32_e32 v35, v35
	s_nop 0
	v_rcp_f32_e32 v34, v34
	s_nop 0
	v_mul_f32_e32 v45, 0xbfb8aa3b, v18
	v_exp_f32_e32 v46, v45
	v_mul_f32_e32 v45, 0xbfb8aa3b, v19
	v_exp_f32_e32 v47, v45
	v_mul_f32_e32 v45, 0xbfb8aa3b, v20
	v_exp_f32_e32 v48, v45
	v_mul_f32_e32 v45, 0xbfb8aa3b, v21
	v_exp_f32_e32 v49, v45
	v_pk_add_f32 v[46:47], v[46:47], 1.0 op_sel_hi:[1,0]
	v_pk_add_f32 v[48:49], v[48:49], 1.0 op_sel_hi:[1,0]
	s_nop 0
	v_rcp_f32_e32 v49, v49
	s_nop 0
	v_rcp_f32_e32 v48, v48
	s_nop 0
	v_rcp_f32_e32 v47, v47
	s_nop 0
	v_div_scale_f32 v45, s[52:53], v46, v46, 1.0
	v_rcp_f32_e32 v51, v45
	s_nop 0
	v_fma_f32 v52, -v45, v51, 1.0
	v_fmac_f32_e32 v51, v52, v51
	v_div_scale_f32 v52, vcc, 1.0, v46, 1.0
	v_mul_f32_e32 v53, v52, v51
	v_fma_f32 v56, -v45, v53, v52
	v_fmac_f32_e32 v53, v56, v51
	v_fma_f32 v45, -v45, v53, v52
	v_div_fmas_f32 v45, v45, v51, v53
	v_add_co_u32_e32 v40, vcc, 0x138fd000, v40
	v_div_fixup_f32 v46, v45, v46, 1.0
	s_nop 0
	v_addc_co_u32_e32 v41, vcc, 0, v41, vcc
	global_store_dwordx4 v[40:41], v[34:37], off offset:3584
	global_store_dwordx4 v[40:41], v[46:49], off offset:3600

.LBB0_612:
	s_andn2_b64 vcc, exec, s[12:13]
	s_cbranch_vccnz .LBB0_614
	v_mul_f32_e32 v34, 0x3d372713, v22
	v_mul_f32_e32 v34, v22, v34
	v_fma_f32 v34, v22, v34, v22
	v_mul_f32_e32 v34, 0xbfcc422a, v34
	v_mul_f32_e32 v34, 0x3fb8aa3b, v34
	v_exp_f32_e32 v34, v34
	s_ashr_i32 s43, s42, 31
	v_ashrrev_i32_e32 v171, 31, v170
	v_add_f32_e32 v34, 1.0, v34
	v_rcp_f32_e32 v35, v34
	s_nop 0
	v_mul_f32_e32 v34, v22, v35
	v_mul_f32_e32 v35, 0x3d372713, v23
	v_mul_f32_e32 v35, v23, v35
	v_fma_f32 v35, v23, v35, v23
	v_mul_f32_e32 v35, 0xbfcc422a, v35
	v_mul_f32_e32 v35, 0x3fb8aa3b, v35
	v_exp_f32_e32 v35, v35
	s_nop 0
	v_add_f32_e32 v35, 1.0, v35
	v_rcp_f32_e32 v36, v35
	s_nop 0
	v_mul_f32_e32 v35, v23, v36
	v_mul_f32_e32 v36, 0x3d372713, v24
	v_mul_f32_e32 v36, v24, v36
	v_fma_f32 v36, v24, v36, v24
	v_mul_f32_e32 v36, 0xbfcc422a, v36
	v_mul_f32_e32 v36, 0x3fb8aa3b, v36
	v_exp_f32_e32 v36, v36
	v_cvt_pk_bf16_f32 v34, v34, v35
	s_nop 0
	v_add_f32_e32 v36, 1.0, v36
	v_rcp_f32_e32 v37, v36
	s_nop 0
	v_mul_f32_e32 v36, v24, v37
	v_mul_f32_e32 v37, 0x3d372713, v25
	v_mul_f32_e32 v37, v25, v37
	v_fma_f32 v37, v25, v37, v25
	v_mul_f32_e32 v37, 0xbfcc422a, v37
	v_mul_f32_e32 v37, 0x3fb8aa3b, v37
	v_exp_f32_e32 v37, v37
	s_nop 0
	v_add_f32_e32 v37, 1.0, v37
	v_rcp_f32_e32 v40, v37
	s_nop 0
	v_mul_f32_e32 v37, v25, v40
	v_mul_f32_e32 v40, 0x3d372713, v18
	v_mul_f32_e32 v40, v18, v40
	v_fma_f32 v40, v18, v40, v18
	v_mul_f32_e32 v40, 0xbfcc422a, v40
	v_mul_f32_e32 v40, 0x3fb8aa3b, v40
	v_exp_f32_e32 v40, v40
	v_cvt_pk_bf16_f32 v35, v36, v37
	s_nop 0
	v_add_f32_e32 v40, 1.0, v40
	v_rcp_f32_e32 v41, v40
	s_nop 0
	v_mul_f32_e32 v40, v18, v41
	v_mul_f32_e32 v41, 0x3d372713, v19
	v_mul_f32_e32 v41, v19, v41
	v_fma_f32 v41, v19, v41, v19
	v_mul_f32_e32 v41, 0xbfcc422a, v41
	v_mul_f32_e32 v41, 0x3fb8aa3b, v41
	v_exp_f32_e32 v41, v41
	s_nop 0
	v_add_f32_e32 v41, 1.0, v41
	v_rcp_f32_e32 v45, v41
	s_nop 0
	v_mul_f32_e32 v41, v19, v45
	v_mul_f32_e32 v45, 0x3d372713, v20
	v_mul_f32_e32 v45, v20, v45
	v_fma_f32 v45, v20, v45, v20
	v_mul_f32_e32 v45, 0xbfcc422a, v45
	v_mul_f32_e32 v45, 0x3fb8aa3b, v45
	v_exp_f32_e32 v45, v45
	v_cvt_pk_bf16_f32 v36, v40, v41
	v_lshl_add_u64 v[40:41], v[170:171], 0, s[42:43]
	v_readlane_b32 s43, v255, 41
	v_add_f32_e32 v45, 1.0, v45
	v_div_scale_f32 v46, s[12:13], v45, v45, v20
	v_rcp_f32_e32 v47, v46
	v_lshl_add_u64 v[38:39], v[40:41], 1, v[38:39]
	v_fma_f32 v48, -v46, v47, 1.0
	v_fmac_f32_e32 v47, v48, v47
	v_div_scale_f32 v48, vcc, v20, v45, v20
	v_mul_f32_e32 v49, v48, v47
	v_fma_f32 v51, -v46, v49, v48
	v_fmac_f32_e32 v49, v51, v47
	v_fma_f32 v46, -v46, v49, v48
	v_div_fmas_f32 v46, v46, v47, v49
	v_div_fixup_f32 v45, v46, v45, v20
	v_mul_f32_e32 v46, 0x3d372713, v21
	v_mul_f32_e32 v46, v21, v46
	v_fma_f32 v46, v21, v46, v21
	v_mul_f32_e32 v46, 0xbfcc422a, v46
	v_mul_f32_e32 v46, 0x3fb8aa3b, v46
	v_exp_f32_e32 v46, v46
	s_nop 0
	v_add_f32_e32 v46, 1.0, v46
	v_rcp_f32_e32 v47, v46
	s_nop 0
	v_mul_f32_e32 v46, v21, v47
	v_cvt_pk_bf16_f32 v37, v45, v46
	global_store_dwordx4 v[38:39], v[34:37], off offset:256

.LBB0_658:
	v_or_b32_e32 v34, s64, v187
	v_bitop3_b32 v39, s64, v243, v187 bitop3:0xc8
	v_cmp_gt_i32_e64 s[8:9], s76, v34
	v_cmp_lt_i32_e64 s[10:11], s79, v34
	s_and_b64 vcc, exec, s[6:7]
	v_cndmask_b32_e64 v38, v177, v39, s[8:9]
	s_mov_b64 s[6:7], -1
	s_cbranch_vccnz .LBB0_676
	v_add_u32_e32 v16, 0xffffc000, v34
	s_andn2_b64 vcc, exec, s[86:87]
	s_cbranch_vccnz .LBB0_691
	v_ashrrev_i32_e32 v35, 31, v34
	v_mov_b64_e32 v[18:19], s[14:15]
	s_movk_i32 s6, 0x60
	v_mad_i64_i32 v[24:25], s[6:7], v34, s6, v[18:19]
	v_lshlrev_b64 v[18:19], 10, v[34:35]
	v_lshl_add_u64 v[22:23], s[50:51], 0, v[18:19]
	v_cndmask_b32_e64 v18, 0, 1, s[44:45]
	v_cmp_ne_u32_e64 s[12:13], 1, v18
	v_cndmask_b32_e64 v18, 0, 1, s[46:47]
	s_mov_b64 s[50:51], -1
	s_andn2_b64 vcc, exec, s[44:45]
	v_cmp_ne_u32_e64 s[6:7], 1, v18
	s_cbranch_vccnz .LBB0_678
	s_and_b64 vcc, exec, s[6:7]
	s_mov_b64 s[44:45], -1
	s_cbranch_vccnz .LBB0_665
	s_movk_i32 s27, 0x918
	v_cmp_gt_i32_e32 vcc, s27, v170
	s_and_saveexec_b64 s[44:45], vcc
	s_cbranch_execz .LBB0_664
	v_mul_f32_e32 v20, 0xbfb8aa3b, v14
	v_mul_f32_e32 v21, 0xbfb8aa3b, v15
	v_exp_f32_e32 v20, v20
	v_exp_f32_e32 v21, v21
	v_mul_f32_e32 v18, 0xbfb8aa3b, v12
	v_mul_f32_e32 v19, 0xbfb8aa3b, v13
	v_exp_f32_e32 v18, v18
	v_pk_add_f32 v[20:21], v[20:21], 1.0 op_sel_hi:[1,0]
	v_exp_f32_e32 v19, v19
	v_div_scale_f32 v28, s[46:47], v21, v21, 1.0
	v_rcp_f32_e32 v29, v28
	v_pk_add_f32 v[18:19], v[18:19], 1.0 op_sel_hi:[1,0]
	v_mov_b32_e32 v171, v17
	v_lshl_add_u64 v[26:27], v[170:171], 2, v[24:25]
	v_fma_f32 v30, -v28, v29, 1.0
	v_fmac_f32_e32 v29, v30, v29
	v_div_scale_f32 v30, vcc, 1.0, v21, 1.0
	v_mul_f32_e32 v31, v30, v29
	v_fma_f32 v32, -v28, v31, v30
	v_fmac_f32_e32 v31, v32, v29
	v_fma_f32 v28, -v28, v31, v30
	v_div_fmas_f32 v28, v28, v29, v31
	v_div_fixup_f32 v21, v28, v21, 1.0
	v_rcp_f32_e32 v20, v20
	s_nop 0
	v_rcp_f32_e32 v19, v19
	s_nop 0
	v_div_scale_f32 v28, s[46:47], v18, v18, 1.0
	v_rcp_f32_e32 v29, v28
	s_nop 0
	v_fma_f32 v30, -v28, v29, 1.0
	v_fmac_f32_e32 v29, v30, v29
	v_div_scale_f32 v30, vcc, 1.0, v18, 1.0
	v_mul_f32_e32 v31, v30, v29
	v_fma_f32 v32, -v28, v31, v30
	v_fmac_f32_e32 v31, v32, v29
	v_fma_f32 v28, -v28, v31, v30
	v_div_fmas_f32 v28, v28, v29, v31
	v_mul_f32_e32 v30, 0xbfb8aa3b, v10
	v_mul_f32_e32 v31, 0xbfb8aa3b, v11
	v_exp_f32_e32 v30, v30
	v_exp_f32_e32 v31, v31
	v_div_fixup_f32 v18, v28, v18, 1.0
	v_mul_f32_e32 v28, 0xbfb8aa3b, v8
	v_mul_f32_e32 v29, 0xbfb8aa3b, v9
	v_pk_add_f32 v[30:31], v[30:31], 1.0 op_sel_hi:[1,0]
	v_exp_f32_e32 v28, v28
	v_div_scale_f32 v32, s[46:47], v31, v31, 1.0
	v_rcp_f32_e32 v33, v32
	v_exp_f32_e32 v29, v29
	v_fma_f32 v35, -v32, v33, 1.0
	v_fmac_f32_e32 v33, v35, v33
	v_div_scale_f32 v35, vcc, 1.0, v31, 1.0
	v_mul_f32_e32 v36, v35, v33
	v_fma_f32 v37, -v32, v36, v35
	v_fmac_f32_e32 v36, v37, v33
	v_fma_f32 v32, -v32, v36, v35
	v_div_fmas_f32 v32, v32, v33, v36
	v_div_fixup_f32 v31, v32, v31, 1.0
	v_div_scale_f32 v32, s[46:47], v30, v30, 1.0
	v_rcp_f32_e32 v33, v32
	v_pk_add_f32 v[28:29], v[28:29], 1.0 op_sel_hi:[1,0]
	v_fma_f32 v35, -v32, v33, 1.0
	v_fmac_f32_e32 v33, v35, v33
	v_div_scale_f32 v35, vcc, 1.0, v30, 1.0
	v_mul_f32_e32 v36, v35, v33
	v_fma_f32 v37, -v32, v36, v35
	v_fmac_f32_e32 v36, v37, v33
	v_fma_f32 v32, -v32, v36, v35
	v_div_fmas_f32 v32, v32, v33, v36
	v_div_fixup_f32 v30, v32, v30, 1.0
	v_rcp_f32_e32 v29, v29
	s_nop 0
	v_div_scale_f32 v32, s[46:47], v28, v28, 1.0
	v_rcp_f32_e32 v33, v32
	s_nop 0
	v_fma_f32 v35, -v32, v33, 1.0
	v_fmac_f32_e32 v33, v35, v33
	v_div_scale_f32 v35, vcc, 1.0, v28, 1.0
	v_mul_f32_e32 v36, v35, v33
	v_fma_f32 v37, -v32, v36, v35
	v_fmac_f32_e32 v36, v37, v33
	v_fma_f32 v32, -v32, v36, v35
	v_div_fmas_f32 v32, v32, v33, v36
	v_add_co_u32_e32 v26, vcc, 0x138fd000, v26
	v_div_fixup_f32 v28, v32, v28, 1.0
	s_nop 0
	v_addc_co_u32_e32 v27, vcc, 0, v27, vcc
	global_store_dwordx4 v[26:27], v[18:21], off offset:3072
	global_store_dwordx4 v[26:27], v[28:31], off offset:3088

.LBB0_665:
	s_andn2_b64 vcc, exec, s[44:45]
	s_cbranch_vccnz .LBB0_667
	v_mul_f32_e32 v19, 0x3d372713, v12
	v_mul_f32_e32 v19, v12, v19
	v_fma_f32 v19, v12, v19, v12
	v_mul_f32_e32 v19, 0xbfcc422a, v19
	v_mul_f32_e32 v19, 0x3fb8aa3b, v19
	v_exp_f32_e32 v19, v19
	v_add_u32_e32 v18, s42, v170
	v_add_f32_e32 v19, 1.0, v19
	v_rcp_f32_e32 v20, v19
	s_nop 0
	v_mul_f32_e32 v19, v12, v20
	v_mul_f32_e32 v20, 0x3d372713, v13
	v_mul_f32_e32 v20, v13, v20
	v_fma_f32 v20, v13, v20, v13
	v_mul_f32_e32 v20, 0xbfcc422a, v20
	v_mul_f32_e32 v20, 0x3fb8aa3b, v20
	v_exp_f32_e32 v20, v20
	s_nop 0
	v_add_f32_e32 v20, 1.0, v20
	v_rcp_f32_e32 v21, v20
	s_nop 0
	v_mul_f32_e32 v20, v13, v21
	v_mul_f32_e32 v21, 0x3d372713, v14
	v_mul_f32_e32 v21, v14, v21
	v_fma_f32 v21, v14, v21, v14
	v_mul_f32_e32 v21, 0xbfcc422a, v21
	v_mul_f32_e32 v21, 0x3fb8aa3b, v21
	v_exp_f32_e32 v21, v21
	s_nop 0
	v_add_f32_e32 v21, 1.0, v21
	v_rcp_f32_e32 v26, v21
	s_nop 0
	v_mul_f32_e32 v21, v14, v26
	v_mul_f32_e32 v26, 0x3d372713, v15
	v_mul_f32_e32 v26, v15, v26
	v_fma_f32 v26, v15, v26, v15
	v_mul_f32_e32 v26, 0xbfcc422a, v26
	v_mul_f32_e32 v26, 0x3fb8aa3b, v26
	v_exp_f32_e32 v26, v26
	s_nop 0
	v_add_f32_e32 v26, 1.0, v26
	v_rcp_f32_e32 v27, v26
	s_nop 0
	v_mul_f32_e32 v27, v15, v27
	v_mul_f32_e32 v26, 0x3d372713, v8
	v_mul_f32_e32 v26, v8, v26
	v_fma_f32 v26, v8, v26, v8
	v_mul_f32_e32 v26, 0xbfcc422a, v26
	v_mul_f32_e32 v26, 0x3fb8aa3b, v26
	v_exp_f32_e32 v26, v26
	s_nop 0
	v_add_f32_e32 v26, 1.0, v26
	v_rcp_f32_e32 v28, v26
	s_nop 0
	v_mul_f32_e32 v28, v8, v28
	v_mul_f32_e32 v26, 0x3d372713, v9
	v_mul_f32_e32 v26, v9, v26
	v_fma_f32 v26, v9, v26, v9
	v_mul_f32_e32 v26, 0xbfcc422a, v26
	v_mul_f32_e32 v26, 0x3fb8aa3b, v26
	v_exp_f32_e32 v26, v26
	s_nop 0
	v_add_f32_e32 v26, 1.0, v26
	v_rcp_f32_e32 v29, v26
	s_nop 0
	v_mul_f32_e32 v29, v9, v29
	v_mul_f32_e32 v26, 0x3d372713, v10
	v_mul_f32_e32 v26, v10, v26
	v_fma_f32 v26, v10, v26, v10
	v_mul_f32_e32 v26, 0xbfcc422a, v26
	v_mul_f32_e32 v26, 0x3fb8aa3b, v26
	v_exp_f32_e32 v26, v26
	s_nop 0
	v_add_f32_e32 v26, 1.0, v26
	v_rcp_f32_e32 v30, v26
	s_nop 0
	v_mul_f32_e32 v30, v10, v30
	v_mul_f32_e32 v26, 0x3d372713, v11
	v_mul_f32_e32 v26, v11, v26
	v_fma_f32 v26, v11, v26, v11
	v_mul_f32_e32 v26, 0xbfcc422a, v26
	v_mul_f32_e32 v26, 0x3fb8aa3b, v26
	v_exp_f32_e32 v26, v26
	s_nop 0
	v_add_f32_e32 v26, 1.0, v26
	v_rcp_f32_e32 v31, v26
	s_nop 0
	v_mul_f32_e32 v31, v11, v31
	v_cvt_pk_bf16_f32 v26, v19, v20
	v_ashrrev_i32_e32 v19, 31, v18
	v_lshl_add_u64 v[18:19], v[18:19], 1, v[22:23]
	v_cvt_pk_bf16_f32 v27, v21, v27
	v_cvt_pk_bf16_f32 v28, v28, v29
	v_cvt_pk_bf16_f32 v29, v30, v31
	global_store_dwordx4 v[18:19], v[26:29], off

.LBB0_669:
	s_and_b64 vcc, exec, s[6:7]
	s_mov_b64 s[6:7], -1
	s_cbranch_vccnz .LBB0_673
	v_or_b32_e32 v18, 0x80, v170
	s_movk_i32 s6, 0x918
	v_cmp_gt_i32_e32 vcc, s6, v18
	s_and_saveexec_b64 s[6:7], vcc
	s_cbranch_execz .LBB0_672
	v_mul_f32_e32 v20, 0xbfb8aa3b, v6
	v_mul_f32_e32 v21, 0xbfb8aa3b, v7
	v_exp_f32_e32 v20, v20
	v_exp_f32_e32 v21, v21
	v_mul_f32_e32 v18, 0xbfb8aa3b, v4
	v_mul_f32_e32 v19, 0xbfb8aa3b, v5
	v_exp_f32_e32 v18, v18
	v_pk_add_f32 v[20:21], v[20:21], 1.0 op_sel_hi:[1,0]
	v_exp_f32_e32 v19, v19
	v_div_scale_f32 v29, s[12:13], v21, v21, 1.0
	v_rcp_f32_e32 v30, v29
	v_pk_add_f32 v[18:19], v[18:19], 1.0 op_sel_hi:[1,0]
	v_mov_b32_e32 v171, v17
	v_lshl_add_u64 v[24:25], v[170:171], 2, v[24:25]
	v_fma_f32 v31, -v29, v30, 1.0
	v_fmac_f32_e32 v30, v31, v30
	v_div_scale_f32 v31, vcc, 1.0, v21, 1.0
	v_mul_f32_e32 v32, v31, v30
	v_fma_f32 v33, -v29, v32, v31
	v_fmac_f32_e32 v32, v33, v30
	v_fma_f32 v29, -v29, v32, v31
	v_div_fmas_f32 v29, v29, v30, v32
	v_div_fixup_f32 v21, v29, v21, 1.0
	v_rcp_f32_e32 v20, v20
	s_nop 0
	v_rcp_f32_e32 v19, v19
	s_nop 0
	v_rcp_f32_e32 v18, v18
	s_nop 0
	v_mul_f32_e32 v29, 0xbfb8aa3b, v0
	v_exp_f32_e32 v30, v29
	v_mul_f32_e32 v29, 0xbfb8aa3b, v1
	v_exp_f32_e32 v31, v29
	v_mul_f32_e32 v29, 0xbfb8aa3b, v2
	v_exp_f32_e32 v32, v29
	v_mul_f32_e32 v29, 0xbfb8aa3b, v3
	v_exp_f32_e32 v33, v29
	v_pk_add_f32 v[30:31], v[30:31], 1.0 op_sel_hi:[1,0]
	v_pk_add_f32 v[32:33], v[32:33], 1.0 op_sel_hi:[1,0]
	s_nop 0
	v_rcp_f32_e32 v33, v33
	s_nop 0
	v_rcp_f32_e32 v32, v32
	s_nop 0
	v_rcp_f32_e32 v31, v31
	s_nop 0
	v_div_scale_f32 v29, s[12:13], v30, v30, 1.0
	v_rcp_f32_e32 v35, v29
	s_nop 0
	v_fma_f32 v36, -v29, v35, 1.0
	v_fmac_f32_e32 v35, v36, v35
	v_div_scale_f32 v36, vcc, 1.0, v30, 1.0
	v_mul_f32_e32 v37, v36, v35
	v_fma_f32 v40, -v29, v37, v36
	v_fmac_f32_e32 v37, v40, v35
	v_fma_f32 v29, -v29, v37, v36
	v_div_fmas_f32 v29, v29, v35, v37
	v_add_co_u32_e32 v24, vcc, 0x138fd000, v24
	v_div_fixup_f32 v30, v29, v30, 1.0
	s_nop 0
	v_addc_co_u32_e32 v25, vcc, 0, v25, vcc
	global_store_dwordx4 v[24:25], v[18:21], off offset:3584
	global_store_dwordx4 v[24:25], v[30:33], off offset:3600

.LBB0_673:
	s_andn2_b64 vcc, exec, s[6:7]
	s_cbranch_vccnz .LBB0_675
	v_mul_f32_e32 v18, 0x3d372713, v4
	v_mul_f32_e32 v18, v4, v18
	v_fma_f32 v18, v4, v18, v4
	v_mul_f32_e32 v18, 0xbfcc422a, v18
	v_mul_f32_e32 v18, 0x3fb8aa3b, v18
	v_exp_f32_e32 v18, v18
	s_ashr_i32 s43, s42, 31
	v_ashrrev_i32_e32 v171, 31, v170
	v_add_f32_e32 v18, 1.0, v18
	v_rcp_f32_e32 v19, v18
	s_nop 0
	v_mul_f32_e32 v18, v4, v19
	v_mul_f32_e32 v19, 0x3d372713, v5
	v_mul_f32_e32 v19, v5, v19
	v_fma_f32 v19, v5, v19, v5
	v_mul_f32_e32 v19, 0xbfcc422a, v19
	v_mul_f32_e32 v19, 0x3fb8aa3b, v19
	v_exp_f32_e32 v19, v19
	s_nop 0
	v_add_f32_e32 v19, 1.0, v19
	v_rcp_f32_e32 v20, v19
	s_nop 0
	v_mul_f32_e32 v19, v5, v20
	v_mul_f32_e32 v20, 0x3d372713, v6
	v_mul_f32_e32 v20, v6, v20
	v_fma_f32 v20, v6, v20, v6
	v_mul_f32_e32 v20, 0xbfcc422a, v20
	v_mul_f32_e32 v20, 0x3fb8aa3b, v20
	v_exp_f32_e32 v20, v20
	v_cvt_pk_bf16_f32 v18, v18, v19
	s_nop 0
	v_add_f32_e32 v20, 1.0, v20
	v_rcp_f32_e32 v21, v20
	s_nop 0
	v_mul_f32_e32 v20, v6, v21
	v_mul_f32_e32 v21, 0x3d372713, v7
	v_mul_f32_e32 v21, v7, v21
	v_fma_f32 v21, v7, v21, v7
	v_mul_f32_e32 v21, 0xbfcc422a, v21
	v_mul_f32_e32 v21, 0x3fb8aa3b, v21
	v_exp_f32_e32 v21, v21
	s_nop 0
	v_add_f32_e32 v21, 1.0, v21
	v_rcp_f32_e32 v24, v21
	s_nop 0
	v_mul_f32_e32 v21, v7, v24
	v_mul_f32_e32 v24, 0x3d372713, v0
	v_mul_f32_e32 v24, v0, v24
	v_fma_f32 v24, v0, v24, v0
	v_mul_f32_e32 v24, 0xbfcc422a, v24
	v_mul_f32_e32 v24, 0x3fb8aa3b, v24
	v_exp_f32_e32 v24, v24
	v_cvt_pk_bf16_f32 v19, v20, v21
	s_nop 0
	v_add_f32_e32 v24, 1.0, v24
	v_rcp_f32_e32 v25, v24
	s_nop 0
	v_mul_f32_e32 v24, v0, v25
	v_mul_f32_e32 v25, 0x3d372713, v1
	v_mul_f32_e32 v25, v1, v25
	v_fma_f32 v25, v1, v25, v1
	v_mul_f32_e32 v25, 0xbfcc422a, v25
	v_mul_f32_e32 v25, 0x3fb8aa3b, v25
	v_exp_f32_e32 v25, v25
	s_nop 0
	v_add_f32_e32 v25, 1.0, v25
	v_rcp_f32_e32 v29, v25
	s_nop 0
	v_mul_f32_e32 v25, v1, v29
	v_mul_f32_e32 v29, 0x3d372713, v2
	v_mul_f32_e32 v29, v2, v29
	v_fma_f32 v29, v2, v29, v2
	v_mul_f32_e32 v29, 0xbfcc422a, v29
	v_mul_f32_e32 v29, 0x3fb8aa3b, v29
	v_exp_f32_e32 v29, v29
	v_cvt_pk_bf16_f32 v20, v24, v25
	v_lshl_add_u64 v[24:25], v[170:171], 0, s[42:43]
	v_readlane_b32 s43, v255, 41
	v_add_f32_e32 v29, 1.0, v29
	v_div_scale_f32 v30, s[6:7], v29, v29, v2
	v_rcp_f32_e32 v31, v30
	v_lshl_add_u64 v[22:23], v[24:25], 1, v[22:23]
	v_fma_f32 v32, -v30, v31, 1.0
	v_fmac_f32_e32 v31, v32, v31
	v_div_scale_f32 v32, vcc, v2, v29, v2
	v_mul_f32_e32 v33, v32, v31
	v_fma_f32 v35, -v30, v33, v32
	v_fmac_f32_e32 v33, v35, v31
	v_fma_f32 v30, -v30, v33, v32
	v_div_fmas_f32 v30, v30, v31, v33
	v_div_fixup_f32 v29, v30, v29, v2
	v_mul_f32_e32 v30, 0x3d372713, v3
	v_mul_f32_e32 v30, v3, v30
	v_fma_f32 v30, v3, v30, v3
	v_mul_f32_e32 v30, 0xbfcc422a, v30
	v_mul_f32_e32 v30, 0x3fb8aa3b, v30
	v_exp_f32_e32 v30, v30
	s_nop 0
	v_add_f32_e32 v30, 1.0, v30
	v_rcp_f32_e32 v31, v30
	s_nop 0
	v_mul_f32_e32 v30, v3, v31
	v_cvt_pk_bf16_f32 v21, v29, v30
	global_store_dwordx4 v[22:23], v[18:21], off offset:256

.LBB0_2404:
	v_mul_f32_e32 v147, 0xbfb8aa3b, v126
	v_exp_f32_e32 v147, v147
	v_lshl_or_b32 v140, s23, 7, v144
	v_lshl_add_u32 v146, s22, 8, v142
	v_ashrrev_i32_e32 v141, 31, v140
	v_add_f32_e32 v147, 1.0, v147
	v_rcp_f32_e32 v148, v147
	s_nop 0
	v_mul_f32_e32 v126, v126, v148
	v_mul_f32_e32 v122, v126, v122
	v_mul_f32_e32 v126, 0xbfb8aa3b, v127
	v_exp_f32_e32 v126, v126
	s_nop 0
	v_add_f32_e32 v126, 1.0, v126
	v_rcp_f32_e32 v147, v126
	s_nop 0
	v_mul_f32_e32 v126, v127, v147
	v_mul_f32_e32 v123, v126, v123
	v_cvt_pk_bf16_f32 v122, v122, v123
	v_mul_f32_e32 v123, 0xbfb8aa3b, v128
	v_exp_f32_e32 v123, v123
	s_nop 0
	v_add_f32_e32 v123, 1.0, v123
	v_rcp_f32_e32 v126, v123
	s_nop 0
	v_mul_f32_e32 v123, v128, v126
	v_mul_f32_e32 v123, v123, v124
	v_mul_f32_e32 v124, 0xbfb8aa3b, v129
	v_exp_f32_e32 v124, v124
	s_nop 0
	v_add_f32_e32 v124, 1.0, v124
	v_rcp_f32_e32 v126, v124
	s_nop 0
	v_mul_f32_e32 v124, v129, v126
	v_mul_f32_e32 v124, v124, v125
	v_cvt_pk_bf16_f32 v123, v123, v124
	v_mul_f32_e32 v124, 0xbfb8aa3b, v118
	v_exp_f32_e32 v124, v124
	s_nop 0
	v_add_f32_e32 v124, 1.0, v124
	v_rcp_f32_e32 v125, v124
	s_nop 0
	v_mul_f32_e32 v118, v118, v125
	v_mul_f32_e32 v114, v118, v114
	v_mul_f32_e32 v118, 0xbfb8aa3b, v119
	v_exp_f32_e32 v118, v118
	s_nop 0
	v_add_f32_e32 v118, 1.0, v118
	v_rcp_f32_e32 v124, v118
	s_nop 0
	v_mul_f32_e32 v118, v119, v124
	v_mul_f32_e32 v115, v118, v115
	v_cvt_pk_bf16_f32 v124, v114, v115
	v_mul_f32_e32 v114, 0xbfb8aa3b, v120
	v_exp_f32_e32 v114, v114
	s_nop 0
	v_add_f32_e32 v114, 1.0, v114
	v_rcp_f32_e32 v115, v114
	s_nop 0
	v_mul_f32_e32 v114, v120, v115
	v_mul_f32_e32 v115, 0xbfb8aa3b, v121
	v_exp_f32_e32 v115, v115
	v_mul_f32_e32 v114, v114, v116
	v_add_f32_e32 v115, 1.0, v115
	v_rcp_f32_e32 v116, v115
	s_nop 0
	v_mul_f32_e32 v115, v121, v116
	v_mul_f32_e32 v115, v115, v117
	v_cvt_pk_bf16_f32 v125, v114, v115
	v_mov_b64_e32 v[114:115], s[8:9]
	v_mad_i64_i32 v[118:119], s[22:23], v146, s88, v[114:115]
	v_lshlrev_b64 v[116:117], 1, v[140:141]
	v_lshl_add_u64 v[118:119], v[118:119], 0, v[116:117]
	global_store_dwordx4 v[118:119], v[122:125], off
	v_mul_f32_e32 v119, 0xbfb8aa3b, v110
	v_exp_f32_e32 v119, v119
	v_or_b32_e32 v118, 16, v146
	v_add_f32_e32 v119, 1.0, v119
	v_rcp_f32_e32 v120, v119
	s_nop 0
	v_mul_f32_e32 v110, v110, v120
	v_mul_f32_e32 v106, v110, v106
	v_mul_f32_e32 v110, 0xbfb8aa3b, v111
	v_exp_f32_e32 v110, v110
	s_nop 0
	v_add_f32_e32 v110, 1.0, v110
	v_rcp_f32_e32 v119, v110
	s_nop 0
	v_mul_f32_e32 v110, v111, v119
	v_mul_f32_e32 v107, v110, v107
	v_cvt_pk_bf16_f32 v106, v106, v107
	v_mul_f32_e32 v107, 0xbfb8aa3b, v112
	v_exp_f32_e32 v107, v107
	s_nop 0
	v_add_f32_e32 v107, 1.0, v107
	v_rcp_f32_e32 v110, v107
	s_nop 0
	v_mul_f32_e32 v107, v112, v110
	v_mul_f32_e32 v107, v107, v108
	v_mul_f32_e32 v108, 0xbfb8aa3b, v113
	v_exp_f32_e32 v108, v108
	s_nop 0
	v_add_f32_e32 v108, 1.0, v108
	v_rcp_f32_e32 v110, v108
	s_nop 0
	v_mul_f32_e32 v108, v113, v110
	v_mul_f32_e32 v108, v108, v109
	v_cvt_pk_bf16_f32 v107, v107, v108
	v_mul_f32_e32 v108, 0xbfb8aa3b, v102
	v_exp_f32_e32 v108, v108
	s_nop 0
	v_add_f32_e32 v108, 1.0, v108
	v_rcp_f32_e32 v109, v108
	s_nop 0
	v_mul_f32_e32 v102, v102, v109
	v_mul_f32_e32 v98, v102, v98
	v_mul_f32_e32 v102, 0xbfb8aa3b, v103
	v_exp_f32_e32 v102, v102
	s_nop 0
	v_add_f32_e32 v102, 1.0, v102
	v_rcp_f32_e32 v108, v102
	s_nop 0
	v_mul_f32_e32 v102, v103, v108
	v_mul_f32_e32 v99, v102, v99
	v_cvt_pk_bf16_f32 v108, v98, v99
	v_mul_f32_e32 v98, 0xbfb8aa3b, v104
	v_exp_f32_e32 v98, v98
	s_nop 0
	v_add_f32_e32 v98, 1.0, v98
	v_rcp_f32_e32 v99, v98
	s_nop 0
	v_mul_f32_e32 v98, v104, v99
	v_mul_f32_e32 v99, 0xbfb8aa3b, v105
	v_exp_f32_e32 v99, v99
	v_mul_f32_e32 v98, v98, v100
	v_add_f32_e32 v99, 1.0, v99
	v_rcp_f32_e32 v100, v99
	s_nop 0
	v_mul_f32_e32 v99, v105, v100
	v_mul_f32_e32 v99, v99, v101
	v_cvt_pk_bf16_f32 v109, v98, v99
	v_mad_i64_i32 v[98:99], s[22:23], v118, s88, v[114:115]
	v_lshl_add_u64 v[98:99], v[98:99], 0, v[116:117]
	global_store_dwordx4 v[98:99], v[106:109], off
	v_mul_f32_e32 v99, 0xbfb8aa3b, v94
	v_exp_f32_e32 v99, v99
	v_or_b32_e32 v98, 32, v146
	v_add_f32_e32 v99, 1.0, v99
	v_rcp_f32_e32 v100, v99
	s_nop 0
	v_mul_f32_e32 v94, v94, v100
	v_mul_f32_e32 v90, v94, v90
	v_mul_f32_e32 v94, 0xbfb8aa3b, v95
	v_exp_f32_e32 v94, v94
	s_nop 0
	v_add_f32_e32 v94, 1.0, v94
	v_rcp_f32_e32 v99, v94
	s_nop 0
	v_mul_f32_e32 v94, v95, v99
	v_mul_f32_e32 v91, v94, v91
	v_cvt_pk_bf16_f32 v90, v90, v91
	v_mul_f32_e32 v91, 0xbfb8aa3b, v96
	v_exp_f32_e32 v91, v91
	s_nop 0
	v_add_f32_e32 v91, 1.0, v91
	v_rcp_f32_e32 v94, v91
	s_nop 0
	v_mul_f32_e32 v91, v96, v94
	v_mul_f32_e32 v91, v91, v92
	v_mul_f32_e32 v92, 0xbfb8aa3b, v97
	v_exp_f32_e32 v92, v92
	s_nop 0
	v_add_f32_e32 v92, 1.0, v92
	v_rcp_f32_e32 v94, v92
	s_nop 0
	v_mul_f32_e32 v92, v97, v94
	v_mul_f32_e32 v92, v92, v93
	v_cvt_pk_bf16_f32 v91, v91, v92
	v_mul_f32_e32 v92, 0xbfb8aa3b, v86
	v_exp_f32_e32 v92, v92
	s_nop 0
	v_add_f32_e32 v92, 1.0, v92
	v_rcp_f32_e32 v93, v92
	s_nop 0
	v_mul_f32_e32 v86, v86, v93
	v_mul_f32_e32 v82, v86, v82
	v_mul_f32_e32 v86, 0xbfb8aa3b, v87
	v_exp_f32_e32 v86, v86
	s_nop 0
	v_add_f32_e32 v86, 1.0, v86
	v_rcp_f32_e32 v92, v86
	s_nop 0
	v_mul_f32_e32 v86, v87, v92
	v_mul_f32_e32 v83, v86, v83
	v_cvt_pk_bf16_f32 v92, v82, v83
	v_mul_f32_e32 v82, 0xbfb8aa3b, v88
	v_exp_f32_e32 v82, v82
	s_nop 0
	v_add_f32_e32 v82, 1.0, v82
	v_rcp_f32_e32 v83, v82
	s_nop 0
	v_mul_f32_e32 v82, v88, v83
	v_mul_f32_e32 v83, 0xbfb8aa3b, v89
	v_exp_f32_e32 v83, v83
	v_mul_f32_e32 v82, v82, v84
	v_add_f32_e32 v83, 1.0, v83
	v_rcp_f32_e32 v84, v83
	s_nop 0
	v_mul_f32_e32 v83, v89, v84
	v_mul_f32_e32 v83, v83, v85
	v_cvt_pk_bf16_f32 v93, v82, v83
	v_mad_i64_i32 v[82:83], s[22:23], v98, s88, v[114:115]
	v_lshl_add_u64 v[82:83], v[82:83], 0, v[116:117]
	global_store_dwordx4 v[82:83], v[90:93], off
	v_mul_f32_e32 v83, 0xbfb8aa3b, v78
	v_exp_f32_e32 v83, v83
	v_or_b32_e32 v82, 48, v146
	v_add_f32_e32 v83, 1.0, v83
	v_rcp_f32_e32 v84, v83
	s_nop 0
	v_mul_f32_e32 v78, v78, v84
	v_mul_f32_e32 v74, v78, v74
	v_mul_f32_e32 v78, 0xbfb8aa3b, v79
	v_exp_f32_e32 v78, v78
	s_nop 0
	v_add_f32_e32 v78, 1.0, v78
	v_rcp_f32_e32 v83, v78
	s_nop 0
	v_mul_f32_e32 v78, v79, v83
	v_mul_f32_e32 v75, v78, v75
	v_cvt_pk_bf16_f32 v74, v74, v75
	v_mul_f32_e32 v75, 0xbfb8aa3b, v80
	v_exp_f32_e32 v75, v75
	s_nop 0
	v_add_f32_e32 v75, 1.0, v75
	v_rcp_f32_e32 v78, v75
	s_nop 0
	v_mul_f32_e32 v75, v80, v78
	v_mul_f32_e32 v75, v75, v76
	v_mul_f32_e32 v76, 0xbfb8aa3b, v81
	v_exp_f32_e32 v76, v76
	s_nop 0
	v_add_f32_e32 v76, 1.0, v76
	v_rcp_f32_e32 v78, v76
	s_nop 0
	v_mul_f32_e32 v76, v81, v78
	v_mul_f32_e32 v76, v76, v77
	v_cvt_pk_bf16_f32 v75, v75, v76
	v_mul_f32_e32 v76, 0xbfb8aa3b, v70
	v_exp_f32_e32 v76, v76
	s_nop 0
	v_add_f32_e32 v76, 1.0, v76
	v_rcp_f32_e32 v77, v76
	s_nop 0
	v_mul_f32_e32 v70, v70, v77
	v_mul_f32_e32 v66, v70, v66
	v_mul_f32_e32 v70, 0xbfb8aa3b, v71
	v_exp_f32_e32 v70, v70
	s_nop 0
	v_add_f32_e32 v70, 1.0, v70
	v_rcp_f32_e32 v76, v70
	s_nop 0
	v_mul_f32_e32 v70, v71, v76
	v_mul_f32_e32 v67, v70, v67
	v_cvt_pk_bf16_f32 v76, v66, v67
	v_mul_f32_e32 v66, 0xbfb8aa3b, v72
	v_exp_f32_e32 v66, v66
	s_nop 0
	v_add_f32_e32 v66, 1.0, v66
	v_rcp_f32_e32 v67, v66
	s_nop 0
	v_mul_f32_e32 v66, v72, v67
	v_mul_f32_e32 v67, 0xbfb8aa3b, v73
	v_exp_f32_e32 v67, v67
	v_mul_f32_e32 v66, v66, v68
	v_add_f32_e32 v67, 1.0, v67
	v_rcp_f32_e32 v68, v67
	s_nop 0
	v_mul_f32_e32 v67, v73, v68
	v_mul_f32_e32 v67, v67, v69
	v_cvt_pk_bf16_f32 v77, v66, v67
	v_mad_i64_i32 v[66:67], s[22:23], v82, s88, v[114:115]
	v_lshl_add_u64 v[66:67], v[66:67], 0, v[116:117]
	global_store_dwordx4 v[66:67], v[74:77], off
	v_mul_f32_e32 v67, 0xbfb8aa3b, v62
	v_exp_f32_e32 v67, v67
	v_add_u32_e32 v66, 0x80, v146
	v_add_f32_e32 v67, 1.0, v67
	v_rcp_f32_e32 v68, v67
	s_nop 0
	v_mul_f32_e32 v62, v62, v68
	v_mul_f32_e32 v58, v62, v58
	v_mul_f32_e32 v62, 0xbfb8aa3b, v63
	v_exp_f32_e32 v62, v62
	s_nop 0
	v_add_f32_e32 v62, 1.0, v62
	v_rcp_f32_e32 v67, v62
	s_nop 0
	v_mul_f32_e32 v62, v63, v67
	v_mul_f32_e32 v59, v62, v59
	v_cvt_pk_bf16_f32 v58, v58, v59
	v_mul_f32_e32 v59, 0xbfb8aa3b, v64
	v_exp_f32_e32 v59, v59
	s_nop 0
	v_add_f32_e32 v59, 1.0, v59
	v_rcp_f32_e32 v62, v59
	s_nop 0
	v_mul_f32_e32 v59, v64, v62
	v_mul_f32_e32 v59, v59, v60
	v_mul_f32_e32 v60, 0xbfb8aa3b, v65
	v_exp_f32_e32 v60, v60
	s_nop 0
	v_add_f32_e32 v60, 1.0, v60
	v_rcp_f32_e32 v62, v60
	s_nop 0
	v_mul_f32_e32 v60, v65, v62
	v_mul_f32_e32 v60, v60, v61
	v_cvt_pk_bf16_f32 v59, v59, v60
	v_mul_f32_e32 v60, 0xbfb8aa3b, v54
	v_exp_f32_e32 v60, v60
	s_nop 0
	v_add_f32_e32 v60, 1.0, v60
	v_rcp_f32_e32 v61, v60
	s_nop 0
	v_mul_f32_e32 v54, v54, v61
	v_mul_f32_e32 v50, v54, v50
	v_mul_f32_e32 v54, 0xbfb8aa3b, v55
	v_exp_f32_e32 v54, v54
	s_nop 0
	v_add_f32_e32 v54, 1.0, v54
	v_rcp_f32_e32 v60, v54
	s_nop 0
	v_mul_f32_e32 v54, v55, v60
	v_mul_f32_e32 v51, v54, v51
	v_cvt_pk_bf16_f32 v60, v50, v51
	v_mul_f32_e32 v50, 0xbfb8aa3b, v56
	v_exp_f32_e32 v50, v50
	s_nop 0
	v_add_f32_e32 v50, 1.0, v50
	v_rcp_f32_e32 v51, v50
	s_nop 0
	v_mul_f32_e32 v50, v56, v51
	v_mul_f32_e32 v51, 0xbfb8aa3b, v57
	v_exp_f32_e32 v51, v51
	v_mul_f32_e32 v50, v50, v52
	v_add_f32_e32 v51, 1.0, v51
	v_rcp_f32_e32 v52, v51
	s_nop 0
	v_mul_f32_e32 v51, v57, v52
	v_mul_f32_e32 v51, v51, v53
	v_cvt_pk_bf16_f32 v61, v50, v51
	v_mad_i64_i32 v[50:51], s[22:23], v66, s88, v[114:115]
	v_lshl_add_u64 v[50:51], v[50:51], 0, v[116:117]
	global_store_dwordx4 v[50:51], v[58:61], off
	v_mul_f32_e32 v51, 0xbfb8aa3b, v46
	v_exp_f32_e32 v51, v51
	v_add_u32_e32 v50, 0x90, v146
	v_add_f32_e32 v51, 1.0, v51
	v_rcp_f32_e32 v52, v51
	s_nop 0
	v_mul_f32_e32 v46, v46, v52
	v_mul_f32_e32 v42, v46, v42
	v_mul_f32_e32 v46, 0xbfb8aa3b, v47
	v_exp_f32_e32 v46, v46
	s_nop 0
	v_add_f32_e32 v46, 1.0, v46
	v_rcp_f32_e32 v51, v46
	s_nop 0
	v_mul_f32_e32 v46, v47, v51
	v_mul_f32_e32 v43, v46, v43
	v_cvt_pk_bf16_f32 v42, v42, v43
	v_mul_f32_e32 v43, 0xbfb8aa3b, v48
	v_exp_f32_e32 v43, v43
	s_nop 0
	v_add_f32_e32 v43, 1.0, v43
	v_rcp_f32_e32 v46, v43
	s_nop 0
	v_mul_f32_e32 v43, v48, v46
	v_mul_f32_e32 v43, v43, v44
	v_mul_f32_e32 v44, 0xbfb8aa3b, v49
	v_exp_f32_e32 v44, v44
	s_nop 0
	v_add_f32_e32 v44, 1.0, v44
	v_rcp_f32_e32 v46, v44
	s_nop 0
	v_mul_f32_e32 v44, v49, v46
	v_mul_f32_e32 v44, v44, v45
	v_cvt_pk_bf16_f32 v43, v43, v44
	v_mul_f32_e32 v44, 0xbfb8aa3b, v38
	v_exp_f32_e32 v44, v44
	s_nop 0
	v_add_f32_e32 v44, 1.0, v44
	v_rcp_f32_e32 v45, v44
	s_nop 0
	v_mul_f32_e32 v38, v38, v45
	v_mul_f32_e32 v34, v38, v34
	v_mul_f32_e32 v38, 0xbfb8aa3b, v39
	v_exp_f32_e32 v38, v38
	s_nop 0
	v_add_f32_e32 v38, 1.0, v38
	v_rcp_f32_e32 v44, v38
	s_nop 0
	v_mul_f32_e32 v38, v39, v44
	v_mul_f32_e32 v35, v38, v35
	v_cvt_pk_bf16_f32 v44, v34, v35
	v_mul_f32_e32 v34, 0xbfb8aa3b, v40
	v_exp_f32_e32 v34, v34
	s_nop 0
	v_add_f32_e32 v34, 1.0, v34
	v_rcp_f32_e32 v35, v34
	s_nop 0
	v_mul_f32_e32 v34, v40, v35
	v_mul_f32_e32 v35, 0xbfb8aa3b, v41
	v_exp_f32_e32 v35, v35
	v_mul_f32_e32 v34, v34, v36
	v_add_f32_e32 v35, 1.0, v35
	v_rcp_f32_e32 v36, v35
	s_nop 0
	v_mul_f32_e32 v35, v41, v36
	v_mul_f32_e32 v35, v35, v37
	v_cvt_pk_bf16_f32 v45, v34, v35
	v_mad_i64_i32 v[34:35], s[22:23], v50, s88, v[114:115]
	v_lshl_add_u64 v[34:35], v[34:35], 0, v[116:117]
	global_store_dwordx4 v[34:35], v[42:45], off
	v_mul_f32_e32 v35, 0xbfb8aa3b, v30
	v_exp_f32_e32 v35, v35
	v_add_u32_e32 v34, 0xa0, v146
	v_add_f32_e32 v35, 1.0, v35
	v_rcp_f32_e32 v36, v35
	s_nop 0
	v_mul_f32_e32 v30, v30, v36
	v_mul_f32_e32 v26, v30, v26
	v_mul_f32_e32 v30, 0xbfb8aa3b, v31
	v_exp_f32_e32 v30, v30
	s_nop 0
	v_add_f32_e32 v30, 1.0, v30
	v_rcp_f32_e32 v35, v30
	s_nop 0
	v_mul_f32_e32 v30, v31, v35
	v_mul_f32_e32 v27, v30, v27
	v_cvt_pk_bf16_f32 v26, v26, v27
	v_mul_f32_e32 v27, 0xbfb8aa3b, v32
	v_exp_f32_e32 v27, v27
	s_nop 0
	v_add_f32_e32 v27, 1.0, v27
	v_rcp_f32_e32 v30, v27
	s_nop 0
	v_mul_f32_e32 v27, v32, v30
	v_mul_f32_e32 v27, v27, v28
	v_mul_f32_e32 v28, 0xbfb8aa3b, v33
	v_exp_f32_e32 v28, v28
	s_nop 0
	v_add_f32_e32 v28, 1.0, v28
	v_rcp_f32_e32 v30, v28
	s_nop 0
	v_mul_f32_e32 v28, v33, v30
	v_mul_f32_e32 v28, v28, v29
	v_cvt_pk_bf16_f32 v27, v27, v28
	v_mul_f32_e32 v28, 0xbfb8aa3b, v22
	v_exp_f32_e32 v28, v28
	s_nop 0
	v_add_f32_e32 v28, 1.0, v28
	v_rcp_f32_e32 v29, v28
	s_nop 0
	v_mul_f32_e32 v22, v22, v29
	v_mul_f32_e32 v18, v22, v18
	v_mul_f32_e32 v22, 0xbfb8aa3b, v23
	v_exp_f32_e32 v22, v22
	s_nop 0
	v_add_f32_e32 v22, 1.0, v22
	v_rcp_f32_e32 v28, v22
	s_nop 0
	v_mul_f32_e32 v22, v23, v28
	v_mul_f32_e32 v19, v22, v19
	v_cvt_pk_bf16_f32 v28, v18, v19
	v_mul_f32_e32 v18, 0xbfb8aa3b, v24
	v_exp_f32_e32 v18, v18
	s_nop 0
	v_add_f32_e32 v18, 1.0, v18
	v_rcp_f32_e32 v19, v18
	s_nop 0
	v_mul_f32_e32 v18, v24, v19
	v_mul_f32_e32 v19, 0xbfb8aa3b, v25
	v_exp_f32_e32 v19, v19
	v_mul_f32_e32 v18, v18, v20
	v_add_f32_e32 v19, 1.0, v19
	v_rcp_f32_e32 v20, v19
	s_nop 0
	v_mul_f32_e32 v19, v25, v20
	v_mul_f32_e32 v19, v19, v21
	v_cvt_pk_bf16_f32 v29, v18, v19
	v_mad_i64_i32 v[18:19], s[22:23], v34, s88, v[114:115]
	v_lshl_add_u64 v[18:19], v[18:19], 0, v[116:117]
	global_store_dwordx4 v[18:19], v[26:29], off
	v_mul_f32_e32 v19, 0xbfb8aa3b, v12
	v_exp_f32_e32 v19, v19
	v_add_u32_e32 v18, 0xb0, v146
	v_add_f32_e32 v19, 1.0, v19
	v_rcp_f32_e32 v20, v19
	s_nop 0
	v_mul_f32_e32 v12, v12, v20
	v_mul_f32_e32 v8, v12, v8
	v_mul_f32_e32 v12, 0xbfb8aa3b, v13
	v_exp_f32_e32 v12, v12
	s_nop 0
	v_add_f32_e32 v12, 1.0, v12
	v_rcp_f32_e32 v19, v12
	s_nop 0
	v_mul_f32_e32 v12, v13, v19
	v_mul_f32_e32 v9, v12, v9
	v_cvt_pk_bf16_f32 v8, v8, v9
	v_mul_f32_e32 v9, 0xbfb8aa3b, v14
	v_exp_f32_e32 v9, v9
	s_nop 0
	v_add_f32_e32 v9, 1.0, v9
	v_rcp_f32_e32 v12, v9
	s_nop 0
	v_mul_f32_e32 v9, v14, v12
	v_mul_f32_e32 v9, v9, v10
	v_mul_f32_e32 v10, 0xbfb8aa3b, v15
	v_exp_f32_e32 v10, v10
	s_nop 0
	v_add_f32_e32 v10, 1.0, v10
	v_rcp_f32_e32 v12, v10
	s_nop 0
	v_mul_f32_e32 v10, v15, v12
	v_mul_f32_e32 v10, v10, v11
	v_cvt_pk_bf16_f32 v9, v9, v10
	v_mul_f32_e32 v10, 0xbfb8aa3b, v4
	v_exp_f32_e32 v10, v10
	s_nop 0
	v_add_f32_e32 v10, 1.0, v10
	v_rcp_f32_e32 v11, v10
	s_nop 0
	v_mul_f32_e32 v4, v4, v11
	v_mul_f32_e32 v0, v4, v0
	v_mul_f32_e32 v4, 0xbfb8aa3b, v5
	v_exp_f32_e32 v4, v4
	s_nop 0
	v_add_f32_e32 v4, 1.0, v4
	v_rcp_f32_e32 v10, v4
	s_nop 0
	v_mul_f32_e32 v4, v5, v10
	v_mul_f32_e32 v1, v4, v1
	v_cvt_pk_bf16_f32 v10, v0, v1
	v_mul_f32_e32 v0, 0xbfb8aa3b, v6
	v_exp_f32_e32 v0, v0
	s_nop 0
	v_add_f32_e32 v0, 1.0, v0
	v_rcp_f32_e32 v1, v0
	s_nop 0
	v_mul_f32_e32 v0, v6, v1
	v_mul_f32_e32 v1, 0xbfb8aa3b, v7
	v_exp_f32_e32 v1, v1
	v_mul_f32_e32 v0, v0, v2
	v_add_f32_e32 v1, 1.0, v1
	v_rcp_f32_e32 v2, v1
	s_nop 0
	v_mul_f32_e32 v1, v7, v2
	v_mul_f32_e32 v1, v1, v3
	v_cvt_pk_bf16_f32 v11, v0, v1
	v_mad_i64_i32 v[0:1], s[22:23], v18, s88, v[114:115]
	v_lshl_add_u64 v[0:1], v[0:1], 0, v[116:117]
	s_mov_b64 s[22:23], -1
	s_andn2_b64 vcc, exec, s[4:5]
	global_store_dwordx4 v[0:1], v[8:11], off
	s_cbranch_vccnz .LBB0_2393
	s_andn2_b64 vcc, exec, s[6:7]
	s_cbranch_vccnz .LBB0_2392
	s_barrier
	s_branch .LBB0_2392
